# MLA up-projection epilogue: per-row sum-of-squares fetched in two batches at epilogue start instead of 8 serialized round trips
# speedup vs baseline: 1.0193x; 1.0085x over previous
; #define PG8_STAGE(bufoff, gbase, voff) do { _Pragma("unroll") for (int _i = 0; _i < 2; ++_i) \
;         __builtin_amdgcn_global_load_lds((const unsigned*)((const char*)(gbase) + (voff)[_i]), (LAS unsigned*)(lds + (bufoff) + ldsw + _i * 8192), 16, 0, 0); } while (0)
; #define PG8_LDA(dst, b, h) do { _Pragma("unroll") for (int m = 0; m < 4; ++m) _Pragma("unroll") for (int k = 0; k < 2; ++k) dst[m][k] = *(const LAS bf16x8*)(lds + PG8_SA(b, h) + aoff + m * 2048 + k * 1024); } while (0)
; #define PG8_LDB(dst, b, h) do { _Pragma("unroll") for (int n = 0; n < 2; ++n) _Pragma("unroll") for (int k = 0; k < 2; ++k) dst[n][k] = *(const LAS bf16x8*)(lds + PG8_SB(b, h) + boff + n * 2048 + k * 1024); } while (0)
; #define PG8_MMA(ai, bj, At, Bt) do { __builtin_amdgcn_s_setprio(1); _Pragma("unroll") for (int m = 0; m < 4; ++m) _Pragma("unroll") for (int n = 0; n < 2; ++n) _Pragma("unroll") for (int k = 0; k < 2; ++k) \
;         acc[ai][bj][m][n] = __builtin_amdgcn_mfma_f32_16x16x32_bf16(Bt[n][k], At[m][k], acc[ai][bj][m][n], 0, 0, 0); __builtin_amdgcn_s_setprio(0); } while (0)
; #define PG8_WAIT_L(n) asm volatile("s_waitcnt lgkmcnt(" #n ")" ::: "memory")
; #define PG8_BAR __builtin_amdgcn_s_barrier()
; #define PG8_SCHED __builtin_amdgcn_sched_barrier(0)
; template <class Epi, class Sched>
; __device__ __forceinline__ void gemm_phase(LAS unsigned char* lds, const Gemm g, const Sched& S, const Epi& E) {
;     ...
;         for (int t = 0; t < nt; t += 2) {
;             const bool last = (t == nt - 2);
;             const char* a1 = cA + (size_t)(t + 1) * kstep;
;             const char* a2 = last ? nA : cA + (size_t)(t + 2) * kstep; const char* b2 = last ? nB : cB + (size_t)(t + 2) * kstep;
;             const char* a3 = a2 + kstep; const char* b3 = b2 + kstep;
;             PG8_LDB(B0, 0, 0); PG8_SCHED; PG8_LDA(At, 0, 0); PG8_STAGE(PG8_SA(1, 1), a1 + hstepA, voffA);
;             PG8_WAIT_L(8); PG8_BAR; PG8_WAIT_L(0); PG8_MMA(0, 0, At, B0); PG8_BAR; PG8_SCHED;
;             PG8_LDB(B1, 0, 1); PG8_STAGE(PG8_SB(0, 0), b2, voffB);
;             PG8_BAR; PG8_WAIT_L(0); PG8_MMA(0, 1, At, B1); PG8_BAR;
;             PG8_LDA(At, 0, 1); PG8_STAGE(PG8_SA(0, 0), a2, voffA);
;             PG8_BAR; PG8_WAIT_L(0); PG8_MMA(1, 0, At, B0); PG8_BAR; PG8_SCHED;
.LBB0_1427:
	s_add_u32 s0, s10, 0x100
	s_addc_u32 s1, s11, 0
	s_add_i32 s24, 0, 0x10000
	v_add_u32_e32 v0, s24, v164
	ds_read_b128 v[130:133], v0
	ds_read_b128 v[152:155], v0 offset:1024
	ds_read_b128 v[156:159], v0 offset:2048
	ds_read_b128 v[160:163], v0 offset:3072
	s_cmp_eq_u32 s14, 4
	s_cselect_b32 s19, s51, s1
	s_cselect_b32 s18, s50, s0
	s_cselect_b32 s17, s3, s9
	s_cselect_b32 s16, s6, s7
	v_lshl_add_u64 v[194:195], s[10:11], 0, v[150:151]
	s_add_i32 m0, s22, 0xc000
	ds_read_b128 v[166:169], v165
	ds_read_b128 v[170:173], v165 offset:1024
	ds_read_b128 v[174:177], v165 offset:2048
	ds_read_b128 v[178:181], v165 offset:3072
	ds_read_b128 v[182:185], v165 offset:4096
	ds_read_b128 v[186:189], v165 offset:5120
	ds_read_b128 v[190:193], v165 offset:6144
	ds_read_b128 v[198:201], v165 offset:7168
	global_load_lds_dwordx4 v[194:195], off
	v_lshl_add_u64 v[194:195], s[10:11], 0, v[148:149]
	s_add_i32 m0, s22, 0xe000
	s_nop 0
	global_load_lds_dwordx4 v[194:195], off
	s_waitcnt lgkmcnt(8)
	s_barrier
	s_waitcnt lgkmcnt(0)
	s_setprio 1
	s_waitcnt lgkmcnt(0)
	v_mfma_f32_16x16x32_bf16 v[126:129], v[130:133], v[166:169], v[126:129]
	v_mfma_f32_16x16x32_bf16 v[122:125], v[156:159], v[166:169], v[122:125]
	v_mfma_f32_16x16x32_bf16 v[110:113], v[130:133], v[174:177], v[110:113]
	v_mfma_f32_16x16x32_bf16 v[106:109], v[156:159], v[174:177], v[106:109]
	v_mfma_f32_16x16x32_bf16 v[94:97], v[130:133], v[182:185], v[94:97]
	v_mfma_f32_16x16x32_bf16 v[90:93], v[156:159], v[182:185], v[90:93]
	v_mfma_f32_16x16x32_bf16 v[78:81], v[130:133], v[190:193], v[78:81]
	v_mfma_f32_16x16x32_bf16 v[74:77], v[156:159], v[190:193], v[74:77]
	v_mfma_f32_16x16x32_bf16 v[126:129], v[152:155], v[170:173], v[126:129]
	v_mfma_f32_16x16x32_bf16 v[122:125], v[160:163], v[170:173], v[122:125]
	v_mfma_f32_16x16x32_bf16 v[110:113], v[152:155], v[178:181], v[110:113]
	v_mfma_f32_16x16x32_bf16 v[106:109], v[160:163], v[178:181], v[106:109]
	v_mfma_f32_16x16x32_bf16 v[94:97], v[152:155], v[186:189], v[94:97]
	v_mfma_f32_16x16x32_bf16 v[90:93], v[160:163], v[186:189], v[90:93]
	v_mfma_f32_16x16x32_bf16 v[78:81], v[152:155], v[198:201], v[78:81]
	v_mfma_f32_16x16x32_bf16 v[74:77], v[160:163], v[198:201], v[74:77]
	s_setprio 0
	s_barrier
	s_add_i32 s25, 0, 0x14000
	s_add_i32 s10, s24, s21
	v_add_u32_e32 v0, s25, v164
	v_lshl_add_u64 v[194:195], s[16:17], 0, v[136:137]
	s_mov_b32 m0, s10
	ds_read_b128 v[202:205], v0
	ds_read_b128 v[206:209], v0 offset:1024
	ds_read_b128 v[224:227], v0 offset:2048
	ds_read_b128 v[228:231], v0 offset:3072
	global_load_lds_dwordx4 v[194:195], off
	v_lshl_add_u64 v[196:197], s[16:17], 0, v[140:141]
	s_add_i32 m0, s10, 0x2000
	s_nop 0
	global_load_lds_dwordx4 v[196:197], off
	s_barrier
	s_waitcnt lgkmcnt(0)
	s_setprio 1
	s_waitcnt lgkmcnt(0)
	v_mfma_f32_16x16x32_bf16 v[118:121], v[202:205], v[166:169], v[118:121]
	v_mfma_f32_16x16x32_bf16 v[114:117], v[224:227], v[166:169], v[114:117]
	v_mfma_f32_16x16x32_bf16 v[102:105], v[202:205], v[174:177], v[102:105]
	v_mfma_f32_16x16x32_bf16 v[98:101], v[224:227], v[174:177], v[98:101]
	v_mfma_f32_16x16x32_bf16 v[86:89], v[202:205], v[182:185], v[86:89]
	v_mfma_f32_16x16x32_bf16 v[82:85], v[224:227], v[182:185], v[82:85]
	v_mfma_f32_16x16x32_bf16 v[70:73], v[202:205], v[190:193], v[70:73]
	v_mfma_f32_16x16x32_bf16 v[66:69], v[224:227], v[190:193], v[66:69]
	v_mfma_f32_16x16x32_bf16 v[118:121], v[206:209], v[170:173], v[118:121]
	v_mfma_f32_16x16x32_bf16 v[114:117], v[228:231], v[170:173], v[114:117]
	v_mfma_f32_16x16x32_bf16 v[102:105], v[206:209], v[178:181], v[102:105]
	v_mfma_f32_16x16x32_bf16 v[98:101], v[228:231], v[178:181], v[98:101]
	v_mfma_f32_16x16x32_bf16 v[86:89], v[206:209], v[186:189], v[86:89]
	v_mfma_f32_16x16x32_bf16 v[82:85], v[228:231], v[186:189], v[82:85]
	v_mfma_f32_16x16x32_bf16 v[70:73], v[206:209], v[198:201], v[70:73]
	v_mfma_f32_16x16x32_bf16 v[66:69], v[228:231], v[198:201], v[66:69]
	s_setprio 0
	s_mov_b32 m0, s22
	v_lshl_add_u64 v[232:233], s[18:19], 0, v[134:135]
	s_barrier
	ds_read_b128 v[166:169], v165 offset:16384
	ds_read_b128 v[170:173], v165 offset:17408
	ds_read_b128 v[174:177], v165 offset:18432
	ds_read_b128 v[178:181], v165 offset:19456
	ds_read_b128 v[182:185], v165 offset:20480
	ds_read_b128 v[186:189], v165 offset:21504
	ds_read_b128 v[190:193], v165 offset:22528
	ds_read_b128 v[198:201], v165 offset:23552
	global_load_lds_dwordx4 v[232:233], off
	v_lshl_add_u64 v[234:235], s[18:19], 0, v[138:139]
	s_mov_b32 m0, s23
	s_nop 0
	global_load_lds_dwordx4 v[234:235], off
	s_barrier
	s_waitcnt lgkmcnt(0)
	s_setprio 1
	s_waitcnt lgkmcnt(0)
	v_mfma_f32_16x16x32_bf16 v[62:65], v[130:133], v[166:169], v[62:65]
	v_mfma_f32_16x16x32_bf16 v[58:61], v[156:159], v[166:169], v[58:61]
	v_mfma_f32_16x16x32_bf16 v[46:49], v[130:133], v[174:177], v[46:49]
	v_mfma_f32_16x16x32_bf16 v[42:45], v[156:159], v[174:177], v[42:45]
	v_mfma_f32_16x16x32_bf16 v[30:33], v[130:133], v[182:185], v[30:33]
	v_mfma_f32_16x16x32_bf16 v[26:29], v[156:159], v[182:185], v[26:29]
	v_mfma_f32_16x16x32_bf16 v[14:17], v[130:133], v[190:193], v[14:17]
	v_mfma_f32_16x16x32_bf16 v[10:13], v[156:159], v[190:193], v[10:13]
	v_mfma_f32_16x16x32_bf16 v[62:65], v[152:155], v[170:173], v[62:65]
	v_mfma_f32_16x16x32_bf16 v[58:61], v[160:163], v[170:173], v[58:61]
	v_mfma_f32_16x16x32_bf16 v[46:49], v[152:155], v[178:181], v[46:49]
	v_mfma_f32_16x16x32_bf16 v[42:45], v[160:163], v[178:181], v[42:45]
	v_mfma_f32_16x16x32_bf16 v[30:33], v[152:155], v[186:189], v[30:33]
	v_mfma_f32_16x16x32_bf16 v[26:29], v[160:163], v[186:189], v[26:29]
	v_mfma_f32_16x16x32_bf16 v[14:17], v[152:155], v[198:201], v[14:17]
	v_mfma_f32_16x16x32_bf16 v[10:13], v[160:163], v[198:201], v[10:13]
	s_setprio 0
	s_barrier
; #define PG8_STAGE(bufoff, gbase, voff) do { _Pragma("unroll") for (int _i = 0; _i < 2; ++_i) \
;         __builtin_amdgcn_global_load_lds((const unsigned*)((const char*)(gbase) + (voff)[_i]), (LAS unsigned*)(lds + (bufoff) + ldsw + _i * 8192), 16, 0, 0); } while (0)
; #define PG8_LDA(dst, b, h) do { _Pragma("unroll") for (int m = 0; m < 4; ++m) _Pragma("unroll") for (int k = 0; k < 2; ++k) dst[m][k] = *(const LAS bf16x8*)(lds + PG8_SA(b, h) + aoff + m * 2048 + k * 1024); } while (0)
; #define PG8_LDB(dst, b, h) do { _Pragma("unroll") for (int n = 0; n < 2; ++n) _Pragma("unroll") for (int k = 0; k < 2; ++k) dst[n][k] = *(const LAS bf16x8*)(lds + PG8_SB(b, h) + boff + n * 2048 + k * 1024); } while (0)
; #define PG8_WAIT_V(n) asm volatile("s_waitcnt vmcnt(" #n ")" ::: "memory")
; #define PG8_WAIT_L(n) asm volatile("s_waitcnt lgkmcnt(" #n ")" ::: "memory")
; #define PG8_BAR __builtin_amdgcn_s_barrier()
; #define PG8_SCHED __builtin_amdgcn_sched_barrier(0)
; template <class Epi, class Sched>
; __device__ __forceinline__ void gemm_phase(LAS unsigned char* lds, const Gemm g, const Sched& S, const Epi& E) {
;     ...
;             PG8_LDB(B0, 0, 0); PG8_SCHED; PG8_LDA(At, 0, 0); PG8_STAGE(PG8_SA(1, 1), a1 + hstepA, voffA);
;             PG8_WAIT_L(8); PG8_BAR; PG8_WAIT_L(0); PG8_MMA(0, 0, At, B0); PG8_BAR; PG8_SCHED;
;             PG8_LDB(B1, 0, 1); PG8_STAGE(PG8_SB(0, 0), b2, voffB);
;             PG8_BAR; PG8_WAIT_L(0); PG8_MMA(0, 1, At, B1); PG8_BAR;
;             PG8_LDA(At, 0, 1); PG8_STAGE(PG8_SA(0, 0), a2, voffA);
;             PG8_BAR; PG8_WAIT_L(0); PG8_MMA(1, 0, At, B0); PG8_BAR; PG8_SCHED;
;             PG8_STAGE(PG8_SB(0, 1), b2 + hstepB, voffB);
;             PG8_WAIT_V(6); PG8_BAR; PG8_MMA(1, 1, At, B1); PG8_BAR;
;             PG8_LDB(B0, 1, 0); PG8_SCHED; PG8_LDA(At, 1, 0); PG8_STAGE(PG8_SA(0, 1), a2 + hstepA, voffA);
;             PG8_WAIT_L(8); PG8_BAR; PG8_WAIT_L(0); PG8_MMA(0, 0, At, B0); PG8_BAR; PG8_SCHED;
;             PG8_LDB(B1, 1, 1); PG8_STAGE(PG8_SB(1, 0), b3, voffB);
;             PG8_BAR; PG8_WAIT_L(0); PG8_MMA(0, 1, At, B1); PG8_BAR;
;             PG8_LDA(At, 1, 1); PG8_STAGE(PG8_SA(1, 0), a3, voffA);
;             PG8_BAR; PG8_WAIT_L(0); PG8_MMA(1, 0, At, B0); PG8_BAR; PG8_SCHED;
;             PG8_STAGE(PG8_SB(1, 1), b3 + hstepB, voffB);
;             PG8_WAIT_V(6); PG8_BAR; PG8_MMA(1, 1, At, B1); PG8_BAR;
	s_add_u32 s10, s16, 0x20000
	s_addc_u32 s11, s17, 0
	s_add_i32 s24, s25, s21
	v_lshl_add_u64 v[130:131], s[10:11], 0, v[136:137]
	s_mov_b32 m0, s24
	s_nop 0
	global_load_lds_dwordx4 v[130:131], off
	v_lshl_add_u64 v[130:131], s[10:11], 0, v[140:141]
	s_add_i32 m0, s24, 0x2000
	s_nop 0
	global_load_lds_dwordx4 v[130:131], off
	s_waitcnt vmcnt(6)
	s_barrier
	s_setprio 1
	v_mfma_f32_16x16x32_bf16 v[54:57], v[202:205], v[166:169], v[54:57]
	v_mfma_f32_16x16x32_bf16 v[50:53], v[224:227], v[166:169], v[50:53]
	v_mfma_f32_16x16x32_bf16 v[38:41], v[202:205], v[174:177], v[38:41]
	v_mfma_f32_16x16x32_bf16 v[34:37], v[224:227], v[174:177], v[34:37]
	v_mfma_f32_16x16x32_bf16 v[22:25], v[202:205], v[182:185], v[22:25]
	v_mfma_f32_16x16x32_bf16 v[18:21], v[224:227], v[182:185], v[18:21]
	v_mfma_f32_16x16x32_bf16 v[6:9], v[202:205], v[190:193], v[6:9]
	v_mfma_f32_16x16x32_bf16 v[2:5], v[224:227], v[190:193], v[2:5]
	v_mfma_f32_16x16x32_bf16 v[54:57], v[206:209], v[170:173], v[54:57]
	v_mfma_f32_16x16x32_bf16 v[50:53], v[228:231], v[170:173], v[50:53]
	v_mfma_f32_16x16x32_bf16 v[38:41], v[206:209], v[178:181], v[38:41]
	v_mfma_f32_16x16x32_bf16 v[34:37], v[228:231], v[178:181], v[34:37]
	v_mfma_f32_16x16x32_bf16 v[22:25], v[206:209], v[186:189], v[22:25]
	v_mfma_f32_16x16x32_bf16 v[18:21], v[228:231], v[186:189], v[18:21]
	v_mfma_f32_16x16x32_bf16 v[6:9], v[206:209], v[198:201], v[6:9]
	v_mfma_f32_16x16x32_bf16 v[2:5], v[228:231], v[198:201], v[2:5]
	s_setprio 0
	s_add_i32 s24, 0, 0x18000
	v_add_u32_e32 v0, s24, v164
	s_barrier
	ds_read_b128 v[130:133], v0
	ds_read_b128 v[152:155], v0 offset:1024
	ds_read_b128 v[156:159], v0 offset:2048
	ds_read_b128 v[160:163], v0 offset:3072
	s_add_u32 s10, s18, 0x150000
	s_addc_u32 s11, s19, 0
	s_mov_b32 m0, s58
	v_lshl_add_u64 v[202:203], s[10:11], 0, v[134:135]
	ds_read_b128 v[166:169], v165 offset:32768
	ds_read_b128 v[170:173], v165 offset:33792
	ds_read_b128 v[174:177], v165 offset:34816
	ds_read_b128 v[178:181], v165 offset:35840
	ds_read_b128 v[182:185], v165 offset:36864
	ds_read_b128 v[186:189], v165 offset:37888
	ds_read_b128 v[190:193], v165 offset:38912
	ds_read_b128 v[198:201], v165 offset:39936
	global_load_lds_dwordx4 v[202:203], off
	v_lshl_add_u64 v[202:203], s[10:11], 0, v[138:139]
	s_mov_b32 m0, s59
	s_nop 0
	global_load_lds_dwordx4 v[202:203], off
	s_waitcnt lgkmcnt(8)
	s_barrier
	s_waitcnt lgkmcnt(0)
	s_setprio 1
	s_waitcnt lgkmcnt(0)
	v_mfma_f32_16x16x32_bf16 v[126:129], v[130:133], v[166:169], v[126:129]
	v_mfma_f32_16x16x32_bf16 v[122:125], v[156:159], v[166:169], v[122:125]
	v_mfma_f32_16x16x32_bf16 v[110:113], v[130:133], v[174:177], v[110:113]
	v_mfma_f32_16x16x32_bf16 v[106:109], v[156:159], v[174:177], v[106:109]
	v_mfma_f32_16x16x32_bf16 v[94:97], v[130:133], v[182:185], v[94:97]
	v_mfma_f32_16x16x32_bf16 v[90:93], v[156:159], v[182:185], v[90:93]
	v_mfma_f32_16x16x32_bf16 v[78:81], v[130:133], v[190:193], v[78:81]
	v_mfma_f32_16x16x32_bf16 v[74:77], v[156:159], v[190:193], v[74:77]
	v_mfma_f32_16x16x32_bf16 v[126:129], v[152:155], v[170:173], v[126:129]
	v_mfma_f32_16x16x32_bf16 v[122:125], v[160:163], v[170:173], v[122:125]
	v_mfma_f32_16x16x32_bf16 v[110:113], v[152:155], v[178:181], v[110:113]
	v_mfma_f32_16x16x32_bf16 v[106:109], v[160:163], v[178:181], v[106:109]
	v_mfma_f32_16x16x32_bf16 v[94:97], v[152:155], v[186:189], v[94:97]
	v_mfma_f32_16x16x32_bf16 v[90:93], v[160:163], v[186:189], v[90:93]
	v_mfma_f32_16x16x32_bf16 v[78:81], v[152:155], v[198:201], v[78:81]
	v_mfma_f32_16x16x32_bf16 v[74:77], v[160:163], v[198:201], v[74:77]
	s_setprio 0
	s_barrier
	s_add_i32 s18, 0, 0x1c000
	s_add_i32 s10, s24, s21
	v_add_u32_e32 v0, s18, v164
	v_lshl_add_u64 v[194:195], v[194:195], 0, s[26:27]
	s_mov_b32 m0, s10
	ds_read_b128 v[202:205], v0
	ds_read_b128 v[206:209], v0 offset:1024
	ds_read_b128 v[224:227], v0 offset:2048
	ds_read_b128 v[228:231], v0 offset:3072
	global_load_lds_dwordx4 v[194:195], off
	v_lshl_add_u64 v[194:195], v[196:197], 0, s[26:27]
	s_add_i32 m0, s10, 0x2000
	s_nop 0
	global_load_lds_dwordx4 v[194:195], off
	s_barrier
	s_waitcnt lgkmcnt(0)
	s_setprio 1
	s_waitcnt lgkmcnt(0)
	v_mfma_f32_16x16x32_bf16 v[118:121], v[202:205], v[166:169], v[118:121]
	v_mfma_f32_16x16x32_bf16 v[114:117], v[224:227], v[166:169], v[114:117]
	v_mfma_f32_16x16x32_bf16 v[102:105], v[202:205], v[174:177], v[102:105]
	v_mfma_f32_16x16x32_bf16 v[98:101], v[224:227], v[174:177], v[98:101]
	v_mfma_f32_16x16x32_bf16 v[86:89], v[202:205], v[182:185], v[86:89]
	v_mfma_f32_16x16x32_bf16 v[82:85], v[224:227], v[182:185], v[82:85]
	v_mfma_f32_16x16x32_bf16 v[70:73], v[202:205], v[190:193], v[70:73]
	v_mfma_f32_16x16x32_bf16 v[66:69], v[224:227], v[190:193], v[66:69]
	v_mfma_f32_16x16x32_bf16 v[118:121], v[206:209], v[170:173], v[118:121]
	v_mfma_f32_16x16x32_bf16 v[114:117], v[228:231], v[170:173], v[114:117]
	v_mfma_f32_16x16x32_bf16 v[102:105], v[206:209], v[178:181], v[102:105]
	v_mfma_f32_16x16x32_bf16 v[98:101], v[228:231], v[178:181], v[98:101]
	v_mfma_f32_16x16x32_bf16 v[86:89], v[206:209], v[186:189], v[86:89]
	v_mfma_f32_16x16x32_bf16 v[82:85], v[228:231], v[186:189], v[82:85]
	v_mfma_f32_16x16x32_bf16 v[70:73], v[206:209], v[198:201], v[70:73]
	v_mfma_f32_16x16x32_bf16 v[66:69], v[228:231], v[198:201], v[66:69]
	s_setprio 0
	s_mov_b32 m0, s61
	v_lshl_add_u64 v[194:195], v[232:233], 0, s[26:27]
	s_barrier
	ds_read_b128 v[166:169], v165 offset:49152
	ds_read_b128 v[170:173], v165 offset:50176
	ds_read_b128 v[174:177], v165 offset:51200
	ds_read_b128 v[178:181], v165 offset:52224
	ds_read_b128 v[182:185], v165 offset:53248
	ds_read_b128 v[186:189], v165 offset:54272
	ds_read_b128 v[190:193], v165 offset:55296
	ds_read_b128 v[198:201], v165 offset:56320
	global_load_lds_dwordx4 v[194:195], off
	v_lshl_add_u64 v[194:195], v[234:235], 0, s[26:27]
	s_mov_b32 m0, s62
	s_nop 0
	global_load_lds_dwordx4 v[194:195], off
	s_barrier
; #define PG8_STAGE(bufoff, gbase, voff) do { _Pragma("unroll") for (int _i = 0; _i < 2; ++_i) \
;         __builtin_amdgcn_global_load_lds((const unsigned*)((const char*)(gbase) + (voff)[_i]), (LAS unsigned*)(lds + (bufoff) + ldsw + _i * 8192), 16, 0, 0); } while (0)
; #define PG8_LDA(dst, b, h) do { _Pragma("unroll") for (int m = 0; m < 4; ++m) _Pragma("unroll") for (int k = 0; k < 2; ++k) dst[m][k] = *(const LAS bf16x8*)(lds + PG8_SA(b, h) + aoff + m * 2048 + k * 1024); } while (0)
; #define PG8_LDB(dst, b, h) do { _Pragma("unroll") for (int n = 0; n < 2; ++n) _Pragma("unroll") for (int k = 0; k < 2; ++k) dst[n][k] = *(const LAS bf16x8*)(lds + PG8_SB(b, h) + boff + n * 2048 + k * 1024); } while (0)
; #define PG8_WAIT_V(n) asm volatile("s_waitcnt vmcnt(" #n ")" ::: "memory")
; template <class Epi, class Sched>
; __device__ __forceinline__ void gemm_phase(LAS unsigned char* lds, const Gemm g, const Sched& S, const Epi& E) {
;     ...
;             PG8_LDB(B0, 1, 0); PG8_SCHED; PG8_LDA(At, 1, 0); PG8_STAGE(PG8_SA(0, 1), a2 + hstepA, voffA);
;             PG8_WAIT_L(8); PG8_BAR; PG8_WAIT_L(0); PG8_MMA(0, 0, At, B0); PG8_BAR; PG8_SCHED;
;             PG8_LDB(B1, 1, 1); PG8_STAGE(PG8_SB(1, 0), b3, voffB);
;             PG8_BAR; PG8_WAIT_L(0); PG8_MMA(0, 1, At, B1); PG8_BAR;
;             PG8_LDA(At, 1, 1); PG8_STAGE(PG8_SA(1, 0), a3, voffA);
;             PG8_BAR; PG8_WAIT_L(0); PG8_MMA(1, 0, At, B0); PG8_BAR; PG8_SCHED;
;             PG8_STAGE(PG8_SB(1, 1), b3 + hstepB, voffB);
;             PG8_WAIT_V(6); PG8_BAR; PG8_MMA(1, 1, At, B1); PG8_BAR;
;         }
;         E(acc, cur, wr, wc, fr, fq);
;         if (!has_next) break;
;     __device__ __forceinline__ float ssq8(int row, int which) const { const f32x4 a = *(const f32x4*)(ssqp + row * 16 + which * 8), b = *(const f32x4*)(ssqp + row * 16 + which * 8 + 4); return ((a[0] + a[1]) + (a[2] + a[3])) + ((b[0] + b[1]) + (b[2] + b[3])); }
;     __device__ __forceinline__ void operator()(const AccT& acc, const pg8::Unit& u, int wr, int wc, int fr, int fq) const {
;         const int row0 = u.pm * 256 + wr * 64 + fr;
; #pragma unroll
;         for (int ai = 0; ai < 2; ++ai)
; #pragma unroll
;             for (int m = 0; m < 4; ++m) {
;                 const int row = row0 + ai * 128 + m * 16;
;                 if (u.pn < 4) {
;                     const float rs = rsqrtf(ssq8(row, 0) * (1.0f / 512) + EPSN) * QS_MLA;
	s_waitcnt lgkmcnt(0)
	s_setprio 1
	s_waitcnt lgkmcnt(0)
	v_mfma_f32_16x16x32_bf16 v[62:65], v[130:133], v[166:169], v[62:65]
	v_mfma_f32_16x16x32_bf16 v[58:61], v[156:159], v[166:169], v[58:61]
	v_mfma_f32_16x16x32_bf16 v[46:49], v[130:133], v[174:177], v[46:49]
	v_mfma_f32_16x16x32_bf16 v[42:45], v[156:159], v[174:177], v[42:45]
	v_mfma_f32_16x16x32_bf16 v[30:33], v[130:133], v[182:185], v[30:33]
	v_mfma_f32_16x16x32_bf16 v[26:29], v[156:159], v[182:185], v[26:29]
	v_mfma_f32_16x16x32_bf16 v[14:17], v[130:133], v[190:193], v[14:17]
	v_mfma_f32_16x16x32_bf16 v[10:13], v[156:159], v[190:193], v[10:13]
	v_mfma_f32_16x16x32_bf16 v[62:65], v[152:155], v[170:173], v[62:65]
	v_mfma_f32_16x16x32_bf16 v[58:61], v[160:163], v[170:173], v[58:61]
	v_mfma_f32_16x16x32_bf16 v[46:49], v[152:155], v[178:181], v[46:49]
	v_mfma_f32_16x16x32_bf16 v[42:45], v[160:163], v[178:181], v[42:45]
	v_mfma_f32_16x16x32_bf16 v[30:33], v[152:155], v[186:189], v[30:33]
	v_mfma_f32_16x16x32_bf16 v[26:29], v[160:163], v[186:189], v[26:29]
	v_mfma_f32_16x16x32_bf16 v[14:17], v[152:155], v[198:201], v[14:17]
	v_mfma_f32_16x16x32_bf16 v[10:13], v[160:163], v[198:201], v[10:13]
	s_setprio 0
	s_barrier
	s_add_u32 s10, s16, 0x20080
	s_addc_u32 s11, s17, 0
	s_add_i32 s16, s18, s21
	v_lshl_add_u64 v[130:131], s[10:11], 0, v[136:137]
	s_mov_b32 m0, s16
	s_nop 0
	global_load_lds_dwordx4 v[130:131], off
	v_lshl_add_u64 v[130:131], s[10:11], 0, v[140:141]
	s_add_i32 m0, s16, 0x2000
	s_nop 0
	global_load_lds_dwordx4 v[130:131], off
	s_waitcnt vmcnt(6)
	s_barrier
	s_setprio 1
	v_mfma_f32_16x16x32_bf16 v[54:57], v[202:205], v[166:169], v[54:57]
	v_mfma_f32_16x16x32_bf16 v[50:53], v[224:227], v[166:169], v[50:53]
	v_mfma_f32_16x16x32_bf16 v[38:41], v[202:205], v[174:177], v[38:41]
	v_mfma_f32_16x16x32_bf16 v[34:37], v[224:227], v[174:177], v[34:37]
	v_mfma_f32_16x16x32_bf16 v[22:25], v[202:205], v[182:185], v[22:25]
	v_mfma_f32_16x16x32_bf16 v[18:21], v[224:227], v[182:185], v[18:21]
	v_mfma_f32_16x16x32_bf16 v[6:9], v[202:205], v[190:193], v[6:9]
	v_mfma_f32_16x16x32_bf16 v[2:5], v[224:227], v[190:193], v[2:5]
	v_mfma_f32_16x16x32_bf16 v[54:57], v[206:209], v[170:173], v[54:57]
	v_mfma_f32_16x16x32_bf16 v[50:53], v[228:231], v[170:173], v[50:53]
	v_mfma_f32_16x16x32_bf16 v[38:41], v[206:209], v[178:181], v[38:41]
	v_mfma_f32_16x16x32_bf16 v[34:37], v[228:231], v[178:181], v[34:37]
	v_mfma_f32_16x16x32_bf16 v[22:25], v[206:209], v[186:189], v[22:25]
	v_mfma_f32_16x16x32_bf16 v[18:21], v[228:231], v[186:189], v[18:21]
	v_mfma_f32_16x16x32_bf16 v[6:9], v[206:209], v[198:201], v[6:9]
	v_mfma_f32_16x16x32_bf16 v[2:5], v[228:231], v[198:201], v[2:5]
	s_setprio 0
	s_add_i32 s14, s14, 2
	s_add_u32 s7, s7, 0x100
	s_addc_u32 s9, s9, 0
	s_cmp_gt_u32 s14, 5
	s_mov_b64 s[10:11], s[0:1]
	s_barrier
	s_cbranch_scc0 .LBB0_1427
	s_cmp_gt_i32 s8, 3
	s_cselect_b64 s[10:11], -1, 0
	s_cmp_gt_u32 s8, 5
	s_cselect_b64 s[16:17], -1, 0
	s_lshl_b32 s0, s8, 8
	v_lshl_add_u32 v152, s2, 8, v143
	s_add_i32 s54, s0, 0xfffffa00
	s_lshl_b32 s0, s8, 2
	s_add_i32 s0, s63, s0
	v_lshlrev_b32_e32 v130, 4, v152
	s_mulk_i32 s0, 0xc0
	v_ashrrev_i32_e32 v131, 31, v130
	s_ashr_i32 s55, s54, 31
	s_ashr_i32 s1, s0, 31
	v_lshl_add_u64 v[154:155], v[130:131], 2, s[4:5]
	s_and_b32 s100, s16, 32
	s_mov_b32 s101, 0
	v_lshl_add_u64 v[236:237], v[154:155], 0, s[100:101]
	s_movk_i32 s100, 0x2000
	v_lshl_add_u64 v[238:239], v[236:237], 0, s[100:101]
	global_load_dwordx4 v[194:197], v[236:237], off
	global_load_dwordx4 v[198:201], v[236:237], off offset:16
	global_load_dwordx4 v[202:205], v[236:237], off offset:1024
	global_load_dwordx4 v[206:209], v[236:237], off offset:1040
	global_load_dwordx4 v[224:227], v[236:237], off offset:2048
	global_load_dwordx4 v[228:231], v[236:237], off offset:2064
	global_load_dwordx4 v[240:243], v[236:237], off offset:3072
	global_load_dwordx4 v[244:247], v[236:237], off offset:3088
	s_waitcnt vmcnt(0)
	v_add_f32_e32 v194, v194, v195
	v_add_f32_e32 v196, v196, v197
	v_add_f32_e32 v198, v198, v199
	v_add_f32_e32 v200, v200, v201
	v_add_f32_e32 v202, v202, v203
	v_add_f32_e32 v204, v204, v205
	v_add_f32_e32 v206, v206, v207
	v_add_f32_e32 v208, v208, v209
	v_add_f32_e32 v224, v224, v225
	v_add_f32_e32 v226, v226, v227
	v_add_f32_e32 v228, v228, v229
	v_add_f32_e32 v230, v230, v231
	v_add_f32_e32 v240, v240, v241
	v_add_f32_e32 v242, v242, v243
	v_add_f32_e32 v244, v244, v245
	v_add_f32_e32 v246, v246, v247
	v_add_f32_e32 v194, v194, v196
	v_add_f32_e32 v198, v198, v200
	v_add_f32_e32 v202, v202, v204
	v_add_f32_e32 v206, v206, v208
	v_add_f32_e32 v224, v224, v226
	v_add_f32_e32 v228, v228, v230
	v_add_f32_e32 v240, v240, v242
	v_add_f32_e32 v244, v244, v246
	v_add_f32_e32 v248, v194, v198
	v_add_f32_e32 v249, v202, v206
	v_add_f32_e32 v250, v224, v228
	v_add_f32_e32 v251, v240, v244
	global_load_dwordx4 v[194:197], v[238:239], off
	global_load_dwordx4 v[198:201], v[238:239], off offset:16
	global_load_dwordx4 v[202:205], v[238:239], off offset:1024
	global_load_dwordx4 v[206:209], v[238:239], off offset:1040
	global_load_dwordx4 v[224:227], v[238:239], off offset:2048
	global_load_dwordx4 v[228:231], v[238:239], off offset:2064
	global_load_dwordx4 v[240:243], v[238:239], off offset:3072
	global_load_dwordx4 v[244:247], v[238:239], off offset:3088
	s_waitcnt vmcnt(0)
	v_add_f32_e32 v194, v194, v195
	v_add_f32_e32 v196, v196, v197
	v_add_f32_e32 v198, v198, v199
	v_add_f32_e32 v200, v200, v201
	v_add_f32_e32 v202, v202, v203
	v_add_f32_e32 v204, v204, v205
	v_add_f32_e32 v206, v206, v207
	v_add_f32_e32 v208, v208, v209
	v_add_f32_e32 v224, v224, v225
	v_add_f32_e32 v226, v226, v227
	v_add_f32_e32 v228, v228, v229
	v_add_f32_e32 v230, v230, v231
	v_add_f32_e32 v240, v240, v241
	v_add_f32_e32 v242, v242, v243
	v_add_f32_e32 v244, v244, v245
	v_add_f32_e32 v246, v246, v247
	v_add_f32_e32 v194, v194, v196
	v_add_f32_e32 v198, v198, v200
	v_add_f32_e32 v202, v202, v204
	v_add_f32_e32 v206, v206, v208
	v_add_f32_e32 v224, v224, v226
	v_add_f32_e32 v228, v228, v230
	v_add_f32_e32 v240, v240, v242
	v_add_f32_e32 v244, v244, v246
	v_add_f32_e32 v236, v194, v198
	v_add_f32_e32 v237, v202, v206
	v_add_f32_e32 v238, v224, v228
	v_add_f32_e32 v239, v240, v244
	s_mov_b64 s[18:19], -1
	s_and_b64 vcc, exec, s[10:11]
	s_cbranch_vccz .LBB0_1434
;     __device__ __forceinline__ float ssq8(int row, int which) const { const f32x4 a = *(const f32x4*)(ssqp + row * 16 + which * 8), b = *(const f32x4*)(ssqp + row * 16 + which * 8 + 4); return ((a[0] + a[1]) + (a[2] + a[3])) + ((b[0] + b[1]) + (b[2] + b[3])); }
;     __device__ __forceinline__ void operator()(const AccT& acc, const pg8::Unit& u, int wr, int wc, int fr, int fq) const {
;     ...
;                 if (u.pn < 4) {
;                     const float rs = rsqrtf(ssq8(row, 0) * (1.0f / 512) + EPSN) * QS_MLA;
; #pragma unroll
;                     for (int bj = 0; bj < 2; ++bj)
;                         *(u32x4*)(Qm + (size_t)row * 1536 + (2 * u.pn + bj) * 192 + wc * 32 + 8 * fq) = pack8s(acc[ai][bj][m][0], acc[ai][bj][m][1], rs);
;                 } else if (u.pn < 6) {
;                     const float rs = rsqrtf(ssq8(row, 0) * (1.0f / 512) + EPSN) * QS_MLA;
;                     const int head = 4 * (u.pn - 4) + wc;
;                     const f32x4 c0 = *(const f32x4*)(cosT + row * 32 + 8 * fq), c1 = *(const f32x4*)(cosT + row * 32 + 8 * fq + 4);
;                     const f32x4 s0 = *(const f32x4*)(sinT + row * 32 + 8 * fq), s1 = *(const f32x4*)(sinT + row * 32 + 8 * fq + 4);
;                     const f32x4 x1a = acc[ai][0][m][0] * rs, x1b = acc[ai][0][m][1] * rs, x2a = acc[ai][1][m][0] * rs, x2b = acc[ai][1][m][1] * rs;
;                     const f32x4 y1a = x1a * c0 - x2a * s0, y1b = x1b * c1 - x2b * s1, y2a = x2a * c0 + x1a * s0, y2b = x2b * c1 + x1b * s1;
;                     *(u32x4*)(Qm + (size_t)row * 1536 + head * 192 + 128 + 8 * fq) = pack8s(y1a, y1b, 1.0f);
;                     *(u32x4*)(Qm + (size_t)row * 1536 + head * 192 + 160 + 8 * fq) = pack8s(y2a, y2b, 1.0f);
;                 } else {
;                     const float rs = rsqrtf(ssq8(row, 1) * (1.0f / 512) + EPSN);
; #pragma unroll
;                     for (int bj = 0; bj < 2; ++bj)
;                         *(u32x4*)(KV + (size_t)row * 2048 + (u.pn - 6) * 256 + bj * 128 + wc * 32 + 8 * fq) = pack8s(acc[ai][bj][m][0], acc[ai][bj][m][1], rs);
	s_and_b64 vcc, exec, s[16:17]
	s_cbranch_vccz .LBB0_1431
	s_mov_b32 s2, 0x800000
	v_ashrrev_i32_e32 v153, 31, v152
	s_lshl_b32 s14, s60, 1
	s_mov_b64 s[18:19], 0
	v_lshlrev_b64 v[156:157], 12, v[152:153]
	v_lshl_add_u64 v[156:157], s[46:47], 0, v[156:157]
	v_mov_b32_e32 v0, v248
	v_fmamk_f32 v0, v0, 0x3b000000, v212
	v_cmp_gt_f32_e32 vcc, s2, v0
	v_mul_f32_e32 v130, 0x4b800000, v0
	v_lshl_add_u64 v[156:157], s[54:55], 1, v[156:157]
	v_cndmask_b32_e32 v0, v0, v130, vcc
	v_rsq_f32_e32 v0, v0
	v_lshl_add_u64 v[156:157], v[156:157], 0, s[14:15]
	s_mov_b64 s[2:3], 0x100
	v_mul_f32_e32 v130, 0x45800000, v0
	v_cndmask_b32_e32 v160, v0, v130, vcc
	v_mul_f32_e32 v0, v126, v160
	v_mul_f32_e32 v130, v127, v160
	v_cvt_pk_bf16_f32 v130, v0, v130
	v_mul_f32_e32 v0, v128, v160
	v_mul_f32_e32 v131, v129, v160
	v_cvt_pk_bf16_f32 v131, v0, v131
	v_mul_f32_e32 v0, v122, v160
	v_mul_f32_e32 v132, v123, v160
	v_cvt_pk_bf16_f32 v132, v0, v132
	v_mul_f32_e32 v0, v124, v160
	v_mul_f32_e32 v133, v125, v160
	v_cvt_pk_bf16_f32 v133, v0, v133
	v_lshlrev_b32_e32 v0, 1, v142
	v_lshl_add_u64 v[158:159], v[156:157], 0, v[0:1]
	global_store_dwordx4 v[158:159], v[130:133], off
	v_mul_f32_e32 v0, v118, v160
	v_lshl_add_u64 v[156:157], v[156:157], 0, s[2:3]
	v_mul_f32_e32 v130, v119, v160
	v_cvt_pk_bf16_f32 v130, v0, v130
	v_mul_f32_e32 v0, v120, v160
	v_mul_f32_e32 v131, v121, v160
	v_cvt_pk_bf16_f32 v131, v0, v131
	v_mul_f32_e32 v0, v114, v160
	v_mul_f32_e32 v132, v115, v160
	v_mul_f32_e32 v133, v117, v160
	v_cvt_pk_bf16_f32 v132, v0, v132
	v_mul_f32_e32 v0, v116, v160
	v_cvt_pk_bf16_f32 v133, v0, v133
.LBB0_1431:
	s_andn2_b64 vcc, exec, s[18:19]
	s_cbranch_vccnz .LBB0_1433
	s_mov_b32 s2, 0x800000
	s_nop 0
	s_nop 0
	v_mov_b32_e32 v0, v248
	v_fmamk_f32 v0, v0, 0x3b000000, v212
	v_cmp_gt_f32_e32 vcc, s2, v0
	v_mul_f32_e32 v130, 0x4b800000, v0
	s_movk_i32 s2, 0xc00
	v_cndmask_b32_e32 v0, v0, v130, vcc
	v_rsq_f32_e32 v0, v0
	s_nop 0
	v_mul_f32_e32 v130, 0x45800000, v0
	v_cndmask_b32_e32 v0, v0, v130, vcc
	v_lshlrev_b32_e32 v130, 5, v152
	v_ashrrev_i32_e32 v131, 31, v130
	v_lshlrev_b64 v[160:161], 2, v[130:131]
	v_lshl_add_u64 v[156:157], v[144:145], 0, v[160:161]
	v_lshl_add_u64 v[160:161], v[146:147], 0, v[160:161]
	global_load_dwordx4 v[130:133], v[156:157], off offset:16
	s_nop 0
	global_load_dwordx4 v[156:159], v[156:157], off
	s_nop 0
	global_load_dwordx4 v[166:169], v[160:161], off offset:16
	s_nop 0
	global_load_dwordx4 v[160:163], v[160:161], off
	v_mul_f32_e32 v0, 0x3dd53b94, v0
	v_pk_mul_f32 v[170:171], v[126:127], v[0:1] op_sel_hi:[1,0]
	v_pk_mul_f32 v[172:173], v[128:129], v[0:1] op_sel_hi:[1,0]
	v_pk_mul_f32 v[178:179], v[120:121], v[0:1] op_sel_hi:[1,0]
	v_pk_mul_f32 v[180:181], v[118:119], v[0:1] op_sel_hi:[1,0]
	v_pk_mul_f32 v[174:175], v[122:123], v[0:1] op_sel_hi:[1,0]
	v_pk_mul_f32 v[184:185], v[114:115], v[0:1] op_sel_hi:[1,0]
	v_pk_mul_f32 v[176:177], v[124:125], v[0:1] op_sel_hi:[1,0]
	v_pk_mul_f32 v[182:183], v[116:117], v[0:1] op_sel_hi:[1,0]
	v_lshlrev_b32_e32 v0, 1, v142
	s_waitcnt vmcnt(0)
	v_pk_mul_f32 v[190:191], v[166:167], v[184:185]
	v_pk_mul_f32 v[186:187], v[160:161], v[180:181]
	v_pk_mul_f32 v[188:189], v[162:163], v[178:179]
	v_pk_mul_f32 v[160:161], v[160:161], v[170:171]
	v_pk_mul_f32 v[162:163], v[162:163], v[172:173]
	v_pk_fma_f32 v[188:189], v[158:159], v[172:173], v[188:189] neg_lo:[0,0,1] neg_hi:[0,0,1]
	v_pk_fma_f32 v[158:159], v[158:159], v[178:179], v[162:163]
	v_pk_fma_f32 v[162:163], v[156:157], v[180:181], v[160:161]
	v_pk_mul_f32 v[160:161], v[166:167], v[174:175]
	v_mov_b64_e32 v[166:167], s[44:45]
	v_mad_i64_i32 v[166:167], s[2:3], v152, s2, v[166:167]
	v_pk_fma_f32 v[186:187], v[156:157], v[170:171], v[186:187] neg_lo:[0,0,1] neg_hi:[0,0,1]
	v_pk_mul_f32 v[192:193], v[168:169], v[182:183]
	v_pk_mul_f32 v[156:157], v[168:169], v[176:177]
	v_lshl_add_u64 v[166:167], s[0:1], 1, v[166:167]
	v_pk_fma_f32 v[192:193], v[132:133], v[176:177], v[192:193] neg_lo:[0,0,1] neg_hi:[0,0,1]
	v_pk_fma_f32 v[190:191], v[130:131], v[174:175], v[190:191] neg_lo:[0,0,1] neg_hi:[0,0,1]
	v_pk_fma_f32 v[156:157], v[132:133], v[182:183], v[156:157]
	v_pk_fma_f32 v[160:161], v[130:131], v[184:185], v[160:161]
	v_cvt_pk_bf16_f32 v130, v186, v187
	v_cvt_pk_bf16_f32 v131, v188, v189
	v_cvt_pk_bf16_f32 v132, v190, v191
	v_cvt_pk_bf16_f32 v133, v192, v193
	v_lshl_add_u64 v[168:169], v[166:167], 0, v[0:1]
	s_mov_b64 s[2:3], 0x140
	global_store_dwordx4 v[168:169], v[130:133], off offset:256
	s_nop 1
	v_cvt_pk_bf16_f32 v130, v162, v163
	v_cvt_pk_bf16_f32 v131, v158, v159
	v_cvt_pk_bf16_f32 v132, v160, v161
	v_cvt_pk_bf16_f32 v133, v156, v157
	v_lshl_add_u64 v[156:157], v[166:167], 0, s[2:3]

;     __device__ __forceinline__ float ssq8(int row, int which) const { const f32x4 a = *(const f32x4*)(ssqp + row * 16 + which * 8), b = *(const f32x4*)(ssqp + row * 16 + which * 8 + 4); return ((a[0] + a[1]) + (a[2] + a[3])) + ((b[0] + b[1]) + (b[2] + b[3])); }
;     __device__ __forceinline__ void operator()(const AccT& acc, const pg8::Unit& u, int wr, int wc, int fr, int fq) const {
;     ...
;                 if (u.pn < 4) {
;                     const float rs = rsqrtf(ssq8(row, 0) * (1.0f / 512) + EPSN) * QS_MLA;
; #pragma unroll
;                     for (int bj = 0; bj < 2; ++bj)
;                         *(u32x4*)(Qm + (size_t)row * 1536 + (2 * u.pn + bj) * 192 + wc * 32 + 8 * fq) = pack8s(acc[ai][bj][m][0], acc[ai][bj][m][1], rs);
;                 } else if (u.pn < 6) {
;                     const float rs = rsqrtf(ssq8(row, 0) * (1.0f / 512) + EPSN) * QS_MLA;
;                     const int head = 4 * (u.pn - 4) + wc;
;                     const f32x4 c0 = *(const f32x4*)(cosT + row * 32 + 8 * fq), c1 = *(const f32x4*)(cosT + row * 32 + 8 * fq + 4);
;                     const f32x4 s0 = *(const f32x4*)(sinT + row * 32 + 8 * fq), s1 = *(const f32x4*)(sinT + row * 32 + 8 * fq + 4);
;                     const f32x4 x1a = acc[ai][0][m][0] * rs, x1b = acc[ai][0][m][1] * rs, x2a = acc[ai][1][m][0] * rs, x2b = acc[ai][1][m][1] * rs;
;                     const f32x4 y1a = x1a * c0 - x2a * s0, y1b = x1b * c1 - x2b * s1, y2a = x2a * c0 + x1a * s0, y2b = x2b * c1 + x1b * s1;
;                     *(u32x4*)(Qm + (size_t)row * 1536 + head * 192 + 128 + 8 * fq) = pack8s(y1a, y1b, 1.0f);
;                     *(u32x4*)(Qm + (size_t)row * 1536 + head * 192 + 160 + 8 * fq) = pack8s(y2a, y2b, 1.0f);
;                 } else {
;                     const float rs = rsqrtf(ssq8(row, 1) * (1.0f / 512) + EPSN);
; #pragma unroll
;                     for (int bj = 0; bj < 2; ++bj)
;                         *(u32x4*)(KV + (size_t)row * 2048 + (u.pn - 6) * 256 + bj * 128 + wc * 32 + 8 * fq) = pack8s(acc[ai][bj][m][0], acc[ai][bj][m][1], rs);
.LBB0_1434:
	s_andn2_b64 vcc, exec, s[18:19]
	s_mul_i32 s56, s8, 0x180
	v_lshlrev_b32_e32 v0, 1, v142
	s_cbranch_vccnz .LBB0_1436
	s_nop 0
	s_mov_b32 s2, 0x800000
	s_ashr_i32 s57, s56, 31
	s_lshl_b32 s14, s60, 1
	s_nop 0
	s_nop 0
	v_mov_b32_e32 v130, v248
	v_fmamk_f32 v130, v130, 0x3b000000, v212
	v_cmp_gt_f32_e32 vcc, s2, v130
	v_mul_f32_e32 v131, 0x4b800000, v130
	s_movk_i32 s2, 0xc00
	v_cndmask_b32_e32 v130, v130, v131, vcc
	v_rsq_f32_e32 v130, v130
	s_nop 0
	v_mul_f32_e32 v131, 0x45800000, v130
	v_cndmask_b32_e32 v130, v130, v131, vcc
	v_mul_f32_e32 v133, 0x3dd53b94, v130
	v_mul_f32_e32 v126, v126, v133
	v_mul_f32_e32 v127, v127, v133
	v_cvt_pk_bf16_f32 v126, v126, v127
	v_mul_f32_e32 v127, v128, v133
	v_mul_f32_e32 v128, v129, v133
	v_mul_f32_e32 v122, v122, v133
	v_mul_f32_e32 v123, v123, v133
	v_cvt_pk_bf16_f32 v127, v127, v128
	v_cvt_pk_bf16_f32 v128, v122, v123
	v_mul_f32_e32 v122, v124, v133
	v_mul_f32_e32 v123, v125, v133
	v_cvt_pk_bf16_f32 v129, v122, v123
	v_mov_b64_e32 v[122:123], s[44:45]
	v_mad_i64_i32 v[122:123], s[2:3], v152, s2, v[122:123]
	v_lshl_add_u64 v[122:123], s[56:57], 1, v[122:123]
	v_lshl_add_u64 v[122:123], v[122:123], 0, s[14:15]
	s_mov_b64 s[2:3], 0x180
	v_lshl_add_u64 v[124:125], v[122:123], 0, v[0:1]
	v_mul_f32_e32 v118, v118, v133
	v_mul_f32_e32 v119, v119, v133
	v_mul_f32_e32 v114, v114, v133
	v_mul_f32_e32 v115, v115, v133
	v_lshl_add_u64 v[156:157], v[122:123], 0, s[2:3]
	global_store_dwordx4 v[124:125], v[126:129], off
	v_cvt_pk_bf16_f32 v130, v118, v119
	v_mul_f32_e32 v118, v120, v133
	v_mul_f32_e32 v119, v121, v133
	v_cvt_pk_bf16_f32 v131, v118, v119
	v_cvt_pk_bf16_f32 v132, v114, v115
	v_mul_f32_e32 v114, v116, v133
	v_mul_f32_e32 v115, v117, v133
	v_cvt_pk_bf16_f32 v133, v114, v115
.LBB0_1436:
	v_lshl_add_u64 v[114:115], v[156:157], 0, v[0:1]
	v_or_b32_e32 v118, 16, v152
	global_store_dwordx4 v[114:115], v[130:133], off
	v_lshlrev_b32_e32 v114, 4, v118
	v_ashrrev_i32_e32 v115, 31, v114
	v_lshl_add_u64 v[120:121], v[114:115], 2, s[4:5]
	v_cndmask_b32_e64 v114, 0, 1, s[10:11]
	v_cmp_ne_u32_e64 s[40:41], 1, v114
	v_cndmask_b32_e64 v114, 0, 1, s[16:17]
	s_mov_b64 s[8:9], -1
	s_andn2_b64 vcc, exec, s[10:11]
	v_cmp_ne_u32_e64 s[38:39], 1, v114
	v_readlane_b32 s25, v254, 25
	s_cbranch_vccnz .LBB0_1442
	s_and_b64 vcc, exec, s[38:39]
	s_cbranch_vccnz .LBB0_1439
	s_mov_b32 s2, 0x800000
	v_ashrrev_i32_e32 v119, 31, v118
	s_lshl_b32 s14, s60, 1
	s_mov_b64 s[8:9], 0
	v_lshlrev_b64 v[122:123], 12, v[118:119]
	v_lshl_add_u64 v[122:123], s[46:47], 0, v[122:123]
	v_mov_b32_e32 v114, v249
	v_fmamk_f32 v114, v114, 0x3b000000, v212
	v_cmp_gt_f32_e32 vcc, s2, v114
	v_mul_f32_e32 v115, 0x4b800000, v114
	v_lshl_add_u64 v[122:123], s[54:55], 1, v[122:123]
	v_cndmask_b32_e32 v114, v114, v115, vcc
	v_rsq_f32_e32 v114, v114
	v_lshl_add_u64 v[122:123], v[122:123], 0, s[14:15]
	v_lshl_add_u64 v[124:125], v[122:123], 0, v[0:1]
	s_mov_b64 s[2:3], 0x100
	v_mul_f32_e32 v115, 0x45800000, v114
	v_cndmask_b32_e32 v126, v114, v115, vcc
	v_mul_f32_e32 v114, v110, v126
	v_mul_f32_e32 v115, v111, v126
	v_cvt_pk_bf16_f32 v114, v114, v115
	v_mul_f32_e32 v115, v112, v126
	v_mul_f32_e32 v116, v113, v126
	v_cvt_pk_bf16_f32 v115, v115, v116
	v_mul_f32_e32 v116, v106, v126
	v_mul_f32_e32 v117, v107, v126
	v_cvt_pk_bf16_f32 v116, v116, v117
	v_mul_f32_e32 v117, v108, v126
	v_mul_f32_e32 v119, v109, v126
	v_cvt_pk_bf16_f32 v117, v117, v119
	global_store_dwordx4 v[124:125], v[114:117], off
	v_lshl_add_u64 v[122:123], v[122:123], 0, s[2:3]
	v_mul_f32_e32 v119, v101, v126
	v_mul_f32_e32 v114, v102, v126
	v_mul_f32_e32 v115, v103, v126
	v_cvt_pk_bf16_f32 v114, v114, v115
	v_mul_f32_e32 v115, v104, v126
	v_mul_f32_e32 v116, v105, v126
	v_cvt_pk_bf16_f32 v115, v115, v116
	v_mul_f32_e32 v116, v98, v126
	v_mul_f32_e32 v117, v99, v126
	v_cvt_pk_bf16_f32 v116, v116, v117
	v_mul_f32_e32 v117, v100, v126
	v_cvt_pk_bf16_f32 v117, v117, v119
.LBB0_1439:
	s_andn2_b64 vcc, exec, s[8:9]
	s_cbranch_vccnz .LBB0_1441
	s_mov_b32 s2, 0x800000
	s_nop 0
	s_nop 0
	v_mov_b32_e32 v114, v249
	v_fmamk_f32 v114, v114, 0x3b000000, v212
	v_cmp_gt_f32_e32 vcc, s2, v114
	v_mul_f32_e32 v115, 0x4b800000, v114
	s_movk_i32 s2, 0xc00
	v_cndmask_b32_e32 v114, v114, v115, vcc
	v_rsq_f32_e32 v114, v114
	s_nop 0
	v_mul_f32_e32 v115, 0x45800000, v114
	v_cndmask_b32_e32 v114, v114, v115, vcc
	v_mul_f32_e32 v154, 0x3dd53b94, v114
	v_lshlrev_b32_e32 v114, 5, v118
	v_ashrrev_i32_e32 v115, 31, v114
	v_lshlrev_b64 v[126:127], 2, v[114:115]
	v_lshl_add_u64 v[122:123], v[144:145], 0, v[126:127]
	v_lshl_add_u64 v[126:127], v[146:147], 0, v[126:127]
	global_load_dwordx4 v[114:117], v[122:123], off offset:16
	s_nop 0
	global_load_dwordx4 v[122:125], v[122:123], off
	s_nop 0
	global_load_dwordx4 v[130:133], v[126:127], off offset:16
	s_nop 0
	global_load_dwordx4 v[126:129], v[126:127], off
	v_pk_mul_f32 v[156:157], v[110:111], v[154:155] op_sel_hi:[1,0]
	v_pk_mul_f32 v[158:159], v[112:113], v[154:155] op_sel_hi:[1,0]
	v_pk_mul_f32 v[166:167], v[104:105], v[154:155] op_sel_hi:[1,0]
	v_pk_mul_f32 v[168:169], v[102:103], v[154:155] op_sel_hi:[1,0]
	v_pk_mul_f32 v[160:161], v[106:107], v[154:155] op_sel_hi:[1,0]
	v_pk_mul_f32 v[162:163], v[108:109], v[154:155] op_sel_hi:[1,0]
	v_pk_mul_f32 v[170:171], v[100:101], v[154:155] op_sel_hi:[1,0]
	v_pk_mul_f32 v[154:155], v[98:99], v[154:155] op_sel_hi:[1,0]
	s_waitcnt vmcnt(0)
	v_pk_mul_f32 v[178:179], v[132:133], v[170:171]
	v_pk_mul_f32 v[172:173], v[126:127], v[168:169]
	v_pk_mul_f32 v[174:175], v[128:129], v[166:167]
	v_pk_mul_f32 v[126:127], v[126:127], v[156:157]
	v_pk_mul_f32 v[128:129], v[128:129], v[158:159]
	v_pk_fma_f32 v[174:175], v[124:125], v[158:159], v[174:175] neg_lo:[0,0,1] neg_hi:[0,0,1]
	v_pk_mul_f32 v[176:177], v[130:131], v[154:155]
	v_pk_fma_f32 v[124:125], v[124:125], v[166:167], v[128:129]
	v_pk_fma_f32 v[128:129], v[122:123], v[168:169], v[126:127]
	v_pk_mul_f32 v[126:127], v[130:131], v[160:161]
	v_mov_b64_e32 v[130:131], s[44:45]
	v_mad_i64_i32 v[130:131], s[2:3], v118, s2, v[130:131]
	v_pk_fma_f32 v[172:173], v[122:123], v[156:157], v[172:173] neg_lo:[0,0,1] neg_hi:[0,0,1]
	v_pk_mul_f32 v[122:123], v[132:133], v[162:163]
	v_lshl_add_u64 v[130:131], s[0:1], 1, v[130:131]
	v_pk_fma_f32 v[178:179], v[116:117], v[162:163], v[178:179] neg_lo:[0,0,1] neg_hi:[0,0,1]
	v_pk_fma_f32 v[176:177], v[114:115], v[160:161], v[176:177] neg_lo:[0,0,1] neg_hi:[0,0,1]
	v_pk_fma_f32 v[122:123], v[116:117], v[170:171], v[122:123]
	v_pk_fma_f32 v[126:127], v[114:115], v[154:155], v[126:127]
	v_cvt_pk_bf16_f32 v114, v172, v173
	v_cvt_pk_bf16_f32 v115, v174, v175
	v_cvt_pk_bf16_f32 v116, v176, v177
	v_cvt_pk_bf16_f32 v117, v178, v179
	v_lshl_add_u64 v[132:133], v[130:131], 0, v[0:1]
	s_mov_b64 s[2:3], 0x140
	global_store_dwordx4 v[132:133], v[114:117], off offset:256
	s_nop 1
	v_cvt_pk_bf16_f32 v114, v128, v129
	v_cvt_pk_bf16_f32 v115, v124, v125
	v_cvt_pk_bf16_f32 v116, v126, v127
	v_cvt_pk_bf16_f32 v117, v122, v123
	v_lshl_add_u64 v[122:123], v[130:131], 0, s[2:3]

;     __device__ __forceinline__ float ssq8(int row, int which) const { const f32x4 a = *(const f32x4*)(ssqp + row * 16 + which * 8), b = *(const f32x4*)(ssqp + row * 16 + which * 8 + 4); return ((a[0] + a[1]) + (a[2] + a[3])) + ((b[0] + b[1]) + (b[2] + b[3])); }
;     __device__ __forceinline__ void operator()(const AccT& acc, const pg8::Unit& u, int wr, int wc, int fr, int fq) const {
;     ...
;                 if (u.pn < 4) {
;                     const float rs = rsqrtf(ssq8(row, 0) * (1.0f / 512) + EPSN) * QS_MLA;
; #pragma unroll
;                     for (int bj = 0; bj < 2; ++bj)
;                         *(u32x4*)(Qm + (size_t)row * 1536 + (2 * u.pn + bj) * 192 + wc * 32 + 8 * fq) = pack8s(acc[ai][bj][m][0], acc[ai][bj][m][1], rs);
;                 } else if (u.pn < 6) {
;                     const float rs = rsqrtf(ssq8(row, 0) * (1.0f / 512) + EPSN) * QS_MLA;
;                     const int head = 4 * (u.pn - 4) + wc;
;                     const f32x4 c0 = *(const f32x4*)(cosT + row * 32 + 8 * fq), c1 = *(const f32x4*)(cosT + row * 32 + 8 * fq + 4);
;                     const f32x4 s0 = *(const f32x4*)(sinT + row * 32 + 8 * fq), s1 = *(const f32x4*)(sinT + row * 32 + 8 * fq + 4);
;                     const f32x4 x1a = acc[ai][0][m][0] * rs, x1b = acc[ai][0][m][1] * rs, x2a = acc[ai][1][m][0] * rs, x2b = acc[ai][1][m][1] * rs;
;                     const f32x4 y1a = x1a * c0 - x2a * s0, y1b = x1b * c1 - x2b * s1, y2a = x2a * c0 + x1a * s0, y2b = x2b * c1 + x1b * s1;
;                     *(u32x4*)(Qm + (size_t)row * 1536 + head * 192 + 128 + 8 * fq) = pack8s(y1a, y1b, 1.0f);
;                     *(u32x4*)(Qm + (size_t)row * 1536 + head * 192 + 160 + 8 * fq) = pack8s(y2a, y2b, 1.0f);
;                 } else {
;                     const float rs = rsqrtf(ssq8(row, 1) * (1.0f / 512) + EPSN);
; #pragma unroll
;                     for (int bj = 0; bj < 2; ++bj)
;                         *(u32x4*)(KV + (size_t)row * 2048 + (u.pn - 6) * 256 + bj * 128 + wc * 32 + 8 * fq) = pack8s(acc[ai][bj][m][0], acc[ai][bj][m][1], rs);
.LBB0_1442:
	s_andn2_b64 vcc, exec, s[8:9]
	s_cbranch_vccnz .LBB0_1444
	s_nop 0
	s_mov_b32 s2, 0x800000
	s_ashr_i32 s57, s56, 31
	s_lshl_b32 s14, s60, 1
	s_nop 0
	s_nop 0
	v_mov_b32_e32 v114, v249
	v_fmamk_f32 v114, v114, 0x3b000000, v212
	v_cmp_gt_f32_e32 vcc, s2, v114
	v_mul_f32_e32 v115, 0x4b800000, v114
	s_movk_i32 s2, 0xc00
	v_cndmask_b32_e32 v114, v114, v115, vcc
	v_rsq_f32_e32 v114, v114
	s_nop 0
	v_mul_f32_e32 v115, 0x45800000, v114
	v_cndmask_b32_e32 v114, v114, v115, vcc
	v_mul_f32_e32 v117, 0x3dd53b94, v114
	v_mul_f32_e32 v110, v110, v117
	v_mul_f32_e32 v111, v111, v117
	v_cvt_pk_bf16_f32 v110, v110, v111
	v_mul_f32_e32 v111, v112, v117
	v_mul_f32_e32 v112, v113, v117
	v_mul_f32_e32 v106, v106, v117
	v_mul_f32_e32 v107, v107, v117
	v_cvt_pk_bf16_f32 v111, v111, v112
	v_cvt_pk_bf16_f32 v112, v106, v107
	v_mul_f32_e32 v106, v108, v117
	v_mul_f32_e32 v107, v109, v117
	v_cvt_pk_bf16_f32 v113, v106, v107
	v_mov_b64_e32 v[106:107], s[44:45]
	v_mad_i64_i32 v[106:107], s[2:3], v118, s2, v[106:107]
	v_lshl_add_u64 v[106:107], s[56:57], 1, v[106:107]
	v_lshl_add_u64 v[106:107], v[106:107], 0, s[14:15]
	s_mov_b64 s[2:3], 0x180
	v_lshl_add_u64 v[108:109], v[106:107], 0, v[0:1]
	v_mul_f32_e32 v102, v102, v117
	v_mul_f32_e32 v103, v103, v117
	v_mul_f32_e32 v98, v98, v117
	v_mul_f32_e32 v99, v99, v117
	v_lshl_add_u64 v[122:123], v[106:107], 0, s[2:3]
	global_store_dwordx4 v[108:109], v[110:113], off
	v_cvt_pk_bf16_f32 v114, v102, v103
	v_mul_f32_e32 v102, v104, v117
	v_mul_f32_e32 v103, v105, v117
	v_cvt_pk_bf16_f32 v115, v102, v103
	v_cvt_pk_bf16_f32 v116, v98, v99
	v_mul_f32_e32 v98, v100, v117
	v_mul_f32_e32 v99, v101, v117
	v_cvt_pk_bf16_f32 v117, v98, v99
.LBB0_1444:
	v_lshl_add_u64 v[98:99], v[122:123], 0, v[0:1]
	v_or_b32_e32 v102, 32, v152
	global_store_dwordx4 v[98:99], v[114:117], off
	v_lshlrev_b32_e32 v98, 4, v102
	v_ashrrev_i32_e32 v99, 31, v98
	v_lshl_add_u64 v[104:105], v[98:99], 2, s[4:5]
	s_and_b64 vcc, exec, s[40:41]
	s_mov_b64 s[8:9], -1
	s_cbranch_vccnz .LBB0_1450
	s_and_b64 vcc, exec, s[38:39]
	s_cbranch_vccnz .LBB0_1447
	s_mov_b32 s2, 0x800000
	v_ashrrev_i32_e32 v103, 31, v102
	s_lshl_b32 s14, s60, 1
	s_mov_b64 s[8:9], 0
	v_lshlrev_b64 v[106:107], 12, v[102:103]
	v_lshl_add_u64 v[106:107], s[46:47], 0, v[106:107]
	v_mov_b32_e32 v98, v250
	v_fmamk_f32 v98, v98, 0x3b000000, v212
	v_cmp_gt_f32_e32 vcc, s2, v98
	v_mul_f32_e32 v99, 0x4b800000, v98
	v_lshl_add_u64 v[106:107], s[54:55], 1, v[106:107]
	v_cndmask_b32_e32 v98, v98, v99, vcc
	v_rsq_f32_e32 v98, v98
	v_lshl_add_u64 v[106:107], v[106:107], 0, s[14:15]
	v_lshl_add_u64 v[108:109], v[106:107], 0, v[0:1]
	s_mov_b64 s[2:3], 0x100
	v_mul_f32_e32 v99, 0x45800000, v98
	v_cndmask_b32_e32 v110, v98, v99, vcc
	v_mul_f32_e32 v98, v94, v110
	v_mul_f32_e32 v99, v95, v110
	v_cvt_pk_bf16_f32 v98, v98, v99
	v_mul_f32_e32 v99, v96, v110
	v_mul_f32_e32 v100, v97, v110
	v_cvt_pk_bf16_f32 v99, v99, v100
	v_mul_f32_e32 v100, v90, v110
	v_mul_f32_e32 v101, v91, v110
	v_cvt_pk_bf16_f32 v100, v100, v101
	v_mul_f32_e32 v101, v92, v110
	v_mul_f32_e32 v103, v93, v110
	v_cvt_pk_bf16_f32 v101, v101, v103
	global_store_dwordx4 v[108:109], v[98:101], off
	v_lshl_add_u64 v[106:107], v[106:107], 0, s[2:3]
	v_mul_f32_e32 v103, v85, v110
	v_mul_f32_e32 v98, v86, v110
	v_mul_f32_e32 v99, v87, v110
	v_cvt_pk_bf16_f32 v98, v98, v99
	v_mul_f32_e32 v99, v88, v110
	v_mul_f32_e32 v100, v89, v110
	v_cvt_pk_bf16_f32 v99, v99, v100
	v_mul_f32_e32 v100, v82, v110
	v_mul_f32_e32 v101, v83, v110
	v_cvt_pk_bf16_f32 v100, v100, v101
	v_mul_f32_e32 v101, v84, v110
	v_cvt_pk_bf16_f32 v101, v101, v103
.LBB0_1447:
	s_andn2_b64 vcc, exec, s[8:9]
	s_cbranch_vccnz .LBB0_1449
	s_mov_b32 s2, 0x800000
	s_nop 0
	s_nop 0
	v_mov_b32_e32 v98, v250
	v_fmamk_f32 v98, v98, 0x3b000000, v212
	v_cmp_gt_f32_e32 vcc, s2, v98
	v_mul_f32_e32 v99, 0x4b800000, v98
	s_movk_i32 s2, 0xc00
	v_cndmask_b32_e32 v98, v98, v99, vcc
	v_rsq_f32_e32 v98, v98
	s_nop 0
	v_mul_f32_e32 v99, 0x45800000, v98
	v_cndmask_b32_e32 v98, v98, v99, vcc
	v_mul_f32_e32 v118, 0x3dd53b94, v98
	v_lshlrev_b32_e32 v98, 5, v102
	v_ashrrev_i32_e32 v99, 31, v98
	v_lshlrev_b64 v[110:111], 2, v[98:99]
	v_lshl_add_u64 v[106:107], v[144:145], 0, v[110:111]
	v_lshl_add_u64 v[110:111], v[146:147], 0, v[110:111]
	global_load_dwordx4 v[98:101], v[106:107], off offset:16
	s_nop 0
	global_load_dwordx4 v[106:109], v[106:107], off
	s_nop 0
	global_load_dwordx4 v[114:117], v[110:111], off offset:16
	s_nop 0
	global_load_dwordx4 v[110:113], v[110:111], off
	v_pk_mul_f32 v[120:121], v[94:95], v[118:119] op_sel_hi:[1,0]
	v_pk_mul_f32 v[122:123], v[96:97], v[118:119] op_sel_hi:[1,0]
	v_pk_mul_f32 v[128:129], v[88:89], v[118:119] op_sel_hi:[1,0]
	v_pk_mul_f32 v[130:131], v[86:87], v[118:119] op_sel_hi:[1,0]
	v_pk_mul_f32 v[124:125], v[90:91], v[118:119] op_sel_hi:[1,0]
	v_pk_mul_f32 v[126:127], v[92:93], v[118:119] op_sel_hi:[1,0]
	v_pk_mul_f32 v[132:133], v[84:85], v[118:119] op_sel_hi:[1,0]
	v_pk_mul_f32 v[118:119], v[82:83], v[118:119] op_sel_hi:[1,0]
	s_waitcnt vmcnt(0)
	v_pk_mul_f32 v[160:161], v[116:117], v[132:133]
	v_pk_mul_f32 v[154:155], v[110:111], v[130:131]
	v_pk_mul_f32 v[156:157], v[112:113], v[128:129]
	v_pk_mul_f32 v[110:111], v[110:111], v[120:121]
	v_pk_mul_f32 v[112:113], v[112:113], v[122:123]
	v_pk_fma_f32 v[156:157], v[108:109], v[122:123], v[156:157] neg_lo:[0,0,1] neg_hi:[0,0,1]
	v_pk_mul_f32 v[158:159], v[114:115], v[118:119]
	v_pk_fma_f32 v[108:109], v[108:109], v[128:129], v[112:113]
	v_pk_fma_f32 v[112:113], v[106:107], v[130:131], v[110:111]
	v_pk_mul_f32 v[110:111], v[114:115], v[124:125]
	v_mov_b64_e32 v[114:115], s[44:45]
	v_mad_i64_i32 v[114:115], s[2:3], v102, s2, v[114:115]
	v_pk_fma_f32 v[154:155], v[106:107], v[120:121], v[154:155] neg_lo:[0,0,1] neg_hi:[0,0,1]
	v_pk_mul_f32 v[106:107], v[116:117], v[126:127]
	v_lshl_add_u64 v[114:115], s[0:1], 1, v[114:115]
	v_pk_fma_f32 v[160:161], v[100:101], v[126:127], v[160:161] neg_lo:[0,0,1] neg_hi:[0,0,1]
	v_pk_fma_f32 v[158:159], v[98:99], v[124:125], v[158:159] neg_lo:[0,0,1] neg_hi:[0,0,1]
	v_pk_fma_f32 v[106:107], v[100:101], v[132:133], v[106:107]
	v_pk_fma_f32 v[110:111], v[98:99], v[118:119], v[110:111]
	v_cvt_pk_bf16_f32 v98, v154, v155
	v_cvt_pk_bf16_f32 v99, v156, v157
	v_cvt_pk_bf16_f32 v100, v158, v159
	v_cvt_pk_bf16_f32 v101, v160, v161
	v_lshl_add_u64 v[116:117], v[114:115], 0, v[0:1]
	s_mov_b64 s[2:3], 0x140
	global_store_dwordx4 v[116:117], v[98:101], off offset:256
	s_nop 1
	v_cvt_pk_bf16_f32 v98, v112, v113
	v_cvt_pk_bf16_f32 v99, v108, v109
	v_cvt_pk_bf16_f32 v100, v110, v111
	v_cvt_pk_bf16_f32 v101, v106, v107
	v_lshl_add_u64 v[106:107], v[114:115], 0, s[2:3]

;     __device__ __forceinline__ float ssq8(int row, int which) const { const f32x4 a = *(const f32x4*)(ssqp + row * 16 + which * 8), b = *(const f32x4*)(ssqp + row * 16 + which * 8 + 4); return ((a[0] + a[1]) + (a[2] + a[3])) + ((b[0] + b[1]) + (b[2] + b[3])); }
;     __device__ __forceinline__ void operator()(const AccT& acc, const pg8::Unit& u, int wr, int wc, int fr, int fq) const {
;     ...
;                 if (u.pn < 4) {
;                     const float rs = rsqrtf(ssq8(row, 0) * (1.0f / 512) + EPSN) * QS_MLA;
; #pragma unroll
;                     for (int bj = 0; bj < 2; ++bj)
;                         *(u32x4*)(Qm + (size_t)row * 1536 + (2 * u.pn + bj) * 192 + wc * 32 + 8 * fq) = pack8s(acc[ai][bj][m][0], acc[ai][bj][m][1], rs);
;                 } else if (u.pn < 6) {
;                     const float rs = rsqrtf(ssq8(row, 0) * (1.0f / 512) + EPSN) * QS_MLA;
;                     const int head = 4 * (u.pn - 4) + wc;
;                     const f32x4 c0 = *(const f32x4*)(cosT + row * 32 + 8 * fq), c1 = *(const f32x4*)(cosT + row * 32 + 8 * fq + 4);
;                     const f32x4 s0 = *(const f32x4*)(sinT + row * 32 + 8 * fq), s1 = *(const f32x4*)(sinT + row * 32 + 8 * fq + 4);
;                     const f32x4 x1a = acc[ai][0][m][0] * rs, x1b = acc[ai][0][m][1] * rs, x2a = acc[ai][1][m][0] * rs, x2b = acc[ai][1][m][1] * rs;
;                     const f32x4 y1a = x1a * c0 - x2a * s0, y1b = x1b * c1 - x2b * s1, y2a = x2a * c0 + x1a * s0, y2b = x2b * c1 + x1b * s1;
;                     *(u32x4*)(Qm + (size_t)row * 1536 + head * 192 + 128 + 8 * fq) = pack8s(y1a, y1b, 1.0f);
;                     *(u32x4*)(Qm + (size_t)row * 1536 + head * 192 + 160 + 8 * fq) = pack8s(y2a, y2b, 1.0f);
;                 } else {
;                     const float rs = rsqrtf(ssq8(row, 1) * (1.0f / 512) + EPSN);
; #pragma unroll
;                     for (int bj = 0; bj < 2; ++bj)
;                         *(u32x4*)(KV + (size_t)row * 2048 + (u.pn - 6) * 256 + bj * 128 + wc * 32 + 8 * fq) = pack8s(acc[ai][bj][m][0], acc[ai][bj][m][1], rs);
.LBB0_1450:
	s_andn2_b64 vcc, exec, s[8:9]
	s_cbranch_vccnz .LBB0_1452
	s_nop 0
	s_mov_b32 s2, 0x800000
	s_ashr_i32 s57, s56, 31
	s_lshl_b32 s14, s60, 1
	s_nop 0
	s_nop 0
	v_mov_b32_e32 v98, v250
	v_fmamk_f32 v98, v98, 0x3b000000, v212
	v_cmp_gt_f32_e32 vcc, s2, v98
	v_mul_f32_e32 v99, 0x4b800000, v98
	s_movk_i32 s2, 0xc00
	v_cndmask_b32_e32 v98, v98, v99, vcc
	v_rsq_f32_e32 v98, v98
	s_nop 0
	v_mul_f32_e32 v99, 0x45800000, v98
	v_cndmask_b32_e32 v98, v98, v99, vcc
	v_mul_f32_e32 v101, 0x3dd53b94, v98
	v_mul_f32_e32 v94, v94, v101
	v_mul_f32_e32 v95, v95, v101
	v_cvt_pk_bf16_f32 v94, v94, v95
	v_mul_f32_e32 v95, v96, v101
	v_mul_f32_e32 v96, v97, v101
	v_mul_f32_e32 v90, v90, v101
	v_mul_f32_e32 v91, v91, v101
	v_cvt_pk_bf16_f32 v95, v95, v96
	v_cvt_pk_bf16_f32 v96, v90, v91
	v_mul_f32_e32 v90, v92, v101
	v_mul_f32_e32 v91, v93, v101
	v_cvt_pk_bf16_f32 v97, v90, v91
	v_mov_b64_e32 v[90:91], s[44:45]
	v_mad_i64_i32 v[90:91], s[2:3], v102, s2, v[90:91]
	v_lshl_add_u64 v[90:91], s[56:57], 1, v[90:91]
	v_lshl_add_u64 v[90:91], v[90:91], 0, s[14:15]
	s_mov_b64 s[2:3], 0x180
	v_lshl_add_u64 v[92:93], v[90:91], 0, v[0:1]
	v_mul_f32_e32 v86, v86, v101
	v_mul_f32_e32 v87, v87, v101
	v_mul_f32_e32 v82, v82, v101
	v_mul_f32_e32 v83, v83, v101
	v_lshl_add_u64 v[106:107], v[90:91], 0, s[2:3]
	global_store_dwordx4 v[92:93], v[94:97], off
	v_cvt_pk_bf16_f32 v98, v86, v87
	v_mul_f32_e32 v86, v88, v101
	v_mul_f32_e32 v87, v89, v101
	v_cvt_pk_bf16_f32 v99, v86, v87
	v_cvt_pk_bf16_f32 v100, v82, v83
	v_mul_f32_e32 v82, v84, v101
	v_mul_f32_e32 v83, v85, v101
	v_cvt_pk_bf16_f32 v101, v82, v83
.LBB0_1452:
	v_lshl_add_u64 v[82:83], v[106:107], 0, v[0:1]
	v_or_b32_e32 v86, 48, v152
	global_store_dwordx4 v[82:83], v[98:101], off
	v_lshlrev_b32_e32 v82, 4, v86
	v_ashrrev_i32_e32 v83, 31, v82
	v_lshl_add_u64 v[88:89], v[82:83], 2, s[4:5]
	s_and_b64 vcc, exec, s[40:41]
	s_mov_b64 s[8:9], -1
	s_cbranch_vccnz .LBB0_1458
	s_and_b64 vcc, exec, s[38:39]
	s_cbranch_vccnz .LBB0_1455
	s_mov_b32 s2, 0x800000
	v_ashrrev_i32_e32 v87, 31, v86
	s_lshl_b32 s14, s60, 1
	s_mov_b64 s[8:9], 0
	v_lshlrev_b64 v[90:91], 12, v[86:87]
	v_lshl_add_u64 v[90:91], s[46:47], 0, v[90:91]
	v_mov_b32_e32 v82, v251
	v_fmamk_f32 v82, v82, 0x3b000000, v212
	v_cmp_gt_f32_e32 vcc, s2, v82
	v_mul_f32_e32 v83, 0x4b800000, v82
	v_lshl_add_u64 v[90:91], s[54:55], 1, v[90:91]
	v_cndmask_b32_e32 v82, v82, v83, vcc
	v_rsq_f32_e32 v82, v82
	v_lshl_add_u64 v[90:91], v[90:91], 0, s[14:15]
	v_lshl_add_u64 v[92:93], v[90:91], 0, v[0:1]
	s_mov_b64 s[2:3], 0x100
	v_mul_f32_e32 v83, 0x45800000, v82
	v_cndmask_b32_e32 v94, v82, v83, vcc
	v_mul_f32_e32 v82, v78, v94
	v_mul_f32_e32 v83, v79, v94
	v_cvt_pk_bf16_f32 v82, v82, v83
	v_mul_f32_e32 v83, v80, v94
	v_mul_f32_e32 v84, v81, v94
	v_cvt_pk_bf16_f32 v83, v83, v84
	v_mul_f32_e32 v84, v74, v94
	v_mul_f32_e32 v85, v75, v94
	v_cvt_pk_bf16_f32 v84, v84, v85
	v_mul_f32_e32 v85, v76, v94
	v_mul_f32_e32 v87, v77, v94
	v_cvt_pk_bf16_f32 v85, v85, v87
	global_store_dwordx4 v[92:93], v[82:85], off
	v_lshl_add_u64 v[90:91], v[90:91], 0, s[2:3]
	v_mul_f32_e32 v87, v69, v94
	v_mul_f32_e32 v82, v70, v94
	v_mul_f32_e32 v83, v71, v94
	v_cvt_pk_bf16_f32 v82, v82, v83
	v_mul_f32_e32 v83, v72, v94
	v_mul_f32_e32 v84, v73, v94
	v_cvt_pk_bf16_f32 v83, v83, v84
	v_mul_f32_e32 v84, v66, v94
	v_mul_f32_e32 v85, v67, v94
	v_cvt_pk_bf16_f32 v84, v84, v85
	v_mul_f32_e32 v85, v68, v94
	v_cvt_pk_bf16_f32 v85, v85, v87
.LBB0_1455:
	s_andn2_b64 vcc, exec, s[8:9]
	s_cbranch_vccnz .LBB0_1457
	s_mov_b32 s2, 0x800000
	s_nop 0
	s_nop 0
	v_mov_b32_e32 v82, v251
	v_fmamk_f32 v82, v82, 0x3b000000, v212
	v_cmp_gt_f32_e32 vcc, s2, v82
	v_mul_f32_e32 v83, 0x4b800000, v82
	s_movk_i32 s2, 0xc00
	v_cndmask_b32_e32 v82, v82, v83, vcc
	v_rsq_f32_e32 v82, v82
	s_nop 0
	v_mul_f32_e32 v83, 0x45800000, v82
	v_cndmask_b32_e32 v82, v82, v83, vcc
	v_mul_f32_e32 v102, 0x3dd53b94, v82
	v_lshlrev_b32_e32 v82, 5, v86
	v_ashrrev_i32_e32 v83, 31, v82
	v_lshlrev_b64 v[94:95], 2, v[82:83]
	v_lshl_add_u64 v[90:91], v[144:145], 0, v[94:95]
	v_lshl_add_u64 v[94:95], v[146:147], 0, v[94:95]
	global_load_dwordx4 v[82:85], v[90:91], off offset:16
	s_nop 0
	global_load_dwordx4 v[90:93], v[90:91], off
	s_nop 0
	global_load_dwordx4 v[98:101], v[94:95], off offset:16
	s_nop 0
	global_load_dwordx4 v[94:97], v[94:95], off
	v_pk_mul_f32 v[104:105], v[78:79], v[102:103] op_sel_hi:[1,0]
	v_pk_mul_f32 v[106:107], v[80:81], v[102:103] op_sel_hi:[1,0]
	v_pk_mul_f32 v[112:113], v[72:73], v[102:103] op_sel_hi:[1,0]
	v_pk_mul_f32 v[114:115], v[70:71], v[102:103] op_sel_hi:[1,0]
	v_pk_mul_f32 v[108:109], v[74:75], v[102:103] op_sel_hi:[1,0]
	v_pk_mul_f32 v[110:111], v[76:77], v[102:103] op_sel_hi:[1,0]
	v_pk_mul_f32 v[116:117], v[68:69], v[102:103] op_sel_hi:[1,0]
	v_pk_mul_f32 v[102:103], v[66:67], v[102:103] op_sel_hi:[1,0]
	s_waitcnt vmcnt(0)
	v_pk_mul_f32 v[124:125], v[100:101], v[116:117]
	v_pk_mul_f32 v[118:119], v[94:95], v[114:115]
	v_pk_mul_f32 v[120:121], v[96:97], v[112:113]
	v_pk_mul_f32 v[94:95], v[94:95], v[104:105]
	v_pk_mul_f32 v[96:97], v[96:97], v[106:107]
	v_pk_fma_f32 v[120:121], v[92:93], v[106:107], v[120:121] neg_lo:[0,0,1] neg_hi:[0,0,1]
	v_pk_mul_f32 v[122:123], v[98:99], v[102:103]
	v_pk_fma_f32 v[92:93], v[92:93], v[112:113], v[96:97]
	v_pk_fma_f32 v[96:97], v[90:91], v[114:115], v[94:95]
	v_pk_mul_f32 v[94:95], v[98:99], v[108:109]
	v_mov_b64_e32 v[98:99], s[44:45]
	v_mad_i64_i32 v[98:99], s[2:3], v86, s2, v[98:99]
	v_pk_fma_f32 v[118:119], v[90:91], v[104:105], v[118:119] neg_lo:[0,0,1] neg_hi:[0,0,1]
	v_pk_mul_f32 v[90:91], v[100:101], v[110:111]
	v_lshl_add_u64 v[98:99], s[0:1], 1, v[98:99]
	v_pk_fma_f32 v[124:125], v[84:85], v[110:111], v[124:125] neg_lo:[0,0,1] neg_hi:[0,0,1]
	v_pk_fma_f32 v[122:123], v[82:83], v[108:109], v[122:123] neg_lo:[0,0,1] neg_hi:[0,0,1]
	v_pk_fma_f32 v[90:91], v[84:85], v[116:117], v[90:91]
	v_pk_fma_f32 v[94:95], v[82:83], v[102:103], v[94:95]
	v_cvt_pk_bf16_f32 v82, v118, v119
	v_cvt_pk_bf16_f32 v83, v120, v121
	v_cvt_pk_bf16_f32 v84, v122, v123
	v_cvt_pk_bf16_f32 v85, v124, v125
	v_lshl_add_u64 v[100:101], v[98:99], 0, v[0:1]
	s_mov_b64 s[2:3], 0x140
	global_store_dwordx4 v[100:101], v[82:85], off offset:256
	s_nop 1
	v_cvt_pk_bf16_f32 v82, v96, v97
	v_cvt_pk_bf16_f32 v83, v92, v93
	v_cvt_pk_bf16_f32 v84, v94, v95
	v_cvt_pk_bf16_f32 v85, v90, v91
	v_lshl_add_u64 v[90:91], v[98:99], 0, s[2:3]

;     __device__ __forceinline__ float ssq8(int row, int which) const { const f32x4 a = *(const f32x4*)(ssqp + row * 16 + which * 8), b = *(const f32x4*)(ssqp + row * 16 + which * 8 + 4); return ((a[0] + a[1]) + (a[2] + a[3])) + ((b[0] + b[1]) + (b[2] + b[3])); }
;     __device__ __forceinline__ void operator()(const AccT& acc, const pg8::Unit& u, int wr, int wc, int fr, int fq) const {
;     ...
;                 if (u.pn < 4) {
;                     const float rs = rsqrtf(ssq8(row, 0) * (1.0f / 512) + EPSN) * QS_MLA;
; #pragma unroll
;                     for (int bj = 0; bj < 2; ++bj)
;                         *(u32x4*)(Qm + (size_t)row * 1536 + (2 * u.pn + bj) * 192 + wc * 32 + 8 * fq) = pack8s(acc[ai][bj][m][0], acc[ai][bj][m][1], rs);
;                 } else if (u.pn < 6) {
;                     const float rs = rsqrtf(ssq8(row, 0) * (1.0f / 512) + EPSN) * QS_MLA;
;                     const int head = 4 * (u.pn - 4) + wc;
;                     const f32x4 c0 = *(const f32x4*)(cosT + row * 32 + 8 * fq), c1 = *(const f32x4*)(cosT + row * 32 + 8 * fq + 4);
;                     const f32x4 s0 = *(const f32x4*)(sinT + row * 32 + 8 * fq), s1 = *(const f32x4*)(sinT + row * 32 + 8 * fq + 4);
;                     const f32x4 x1a = acc[ai][0][m][0] * rs, x1b = acc[ai][0][m][1] * rs, x2a = acc[ai][1][m][0] * rs, x2b = acc[ai][1][m][1] * rs;
;                     const f32x4 y1a = x1a * c0 - x2a * s0, y1b = x1b * c1 - x2b * s1, y2a = x2a * c0 + x1a * s0, y2b = x2b * c1 + x1b * s1;
;                     *(u32x4*)(Qm + (size_t)row * 1536 + head * 192 + 128 + 8 * fq) = pack8s(y1a, y1b, 1.0f);
;                     *(u32x4*)(Qm + (size_t)row * 1536 + head * 192 + 160 + 8 * fq) = pack8s(y2a, y2b, 1.0f);
;                 } else {
;                     const float rs = rsqrtf(ssq8(row, 1) * (1.0f / 512) + EPSN);
; #pragma unroll
;                     for (int bj = 0; bj < 2; ++bj)
;                         *(u32x4*)(KV + (size_t)row * 2048 + (u.pn - 6) * 256 + bj * 128 + wc * 32 + 8 * fq) = pack8s(acc[ai][bj][m][0], acc[ai][bj][m][1], rs);
.LBB0_1458:
	s_andn2_b64 vcc, exec, s[8:9]
	s_cbranch_vccnz .LBB0_1460
	s_nop 0
	s_mov_b32 s2, 0x800000
	s_ashr_i32 s57, s56, 31
	s_lshl_b32 s14, s60, 1
	s_nop 0
	s_nop 0
	v_mov_b32_e32 v82, v251
	v_fmamk_f32 v82, v82, 0x3b000000, v212
	v_cmp_gt_f32_e32 vcc, s2, v82
	v_mul_f32_e32 v83, 0x4b800000, v82
	s_movk_i32 s2, 0xc00
	v_cndmask_b32_e32 v82, v82, v83, vcc
	v_rsq_f32_e32 v82, v82
	s_nop 0
	v_mul_f32_e32 v83, 0x45800000, v82
	v_cndmask_b32_e32 v82, v82, v83, vcc
	v_mul_f32_e32 v85, 0x3dd53b94, v82
	v_mul_f32_e32 v78, v78, v85
	v_mul_f32_e32 v79, v79, v85
	v_cvt_pk_bf16_f32 v78, v78, v79
	v_mul_f32_e32 v79, v80, v85
	v_mul_f32_e32 v80, v81, v85
	v_mul_f32_e32 v74, v74, v85
	v_mul_f32_e32 v75, v75, v85
	v_cvt_pk_bf16_f32 v79, v79, v80
	v_cvt_pk_bf16_f32 v80, v74, v75
	v_mul_f32_e32 v74, v76, v85
	v_mul_f32_e32 v75, v77, v85
	v_cvt_pk_bf16_f32 v81, v74, v75
	v_mov_b64_e32 v[74:75], s[44:45]
	v_mad_i64_i32 v[74:75], s[2:3], v86, s2, v[74:75]
	v_lshl_add_u64 v[74:75], s[56:57], 1, v[74:75]
	v_lshl_add_u64 v[74:75], v[74:75], 0, s[14:15]
	s_mov_b64 s[2:3], 0x180
	v_lshl_add_u64 v[76:77], v[74:75], 0, v[0:1]
	v_mul_f32_e32 v70, v70, v85
	v_mul_f32_e32 v71, v71, v85
	v_mul_f32_e32 v66, v66, v85
	v_mul_f32_e32 v67, v67, v85
	v_lshl_add_u64 v[90:91], v[74:75], 0, s[2:3]
	global_store_dwordx4 v[76:77], v[78:81], off
	v_cvt_pk_bf16_f32 v82, v70, v71
	v_mul_f32_e32 v70, v72, v85
	v_mul_f32_e32 v71, v73, v85
	v_cvt_pk_bf16_f32 v83, v70, v71
	v_cvt_pk_bf16_f32 v84, v66, v67
	v_mul_f32_e32 v66, v68, v85
	v_mul_f32_e32 v67, v69, v85
	v_cvt_pk_bf16_f32 v85, v66, v67
.LBB0_1460:
	v_lshl_add_u64 v[66:67], v[90:91], 0, v[0:1]
	v_add_u32_e32 v70, 0x80, v152
	global_store_dwordx4 v[66:67], v[82:85], off
	v_lshlrev_b32_e32 v66, 4, v70
	v_ashrrev_i32_e32 v67, 31, v66
	v_lshl_add_u64 v[72:73], v[66:67], 2, s[4:5]
	s_and_b64 vcc, exec, s[40:41]
	s_mov_b64 s[8:9], -1
	s_cbranch_vccnz .LBB0_1466
	s_and_b64 vcc, exec, s[38:39]
	s_cbranch_vccnz .LBB0_1463
	s_mov_b32 s2, 0x800000
	v_ashrrev_i32_e32 v71, 31, v70
	s_lshl_b32 s14, s60, 1
	s_mov_b64 s[8:9], 0
	v_lshlrev_b64 v[74:75], 12, v[70:71]
	v_lshl_add_u64 v[74:75], s[46:47], 0, v[74:75]
	v_mov_b32_e32 v66, v236
	v_fmamk_f32 v66, v66, 0x3b000000, v212
	v_cmp_gt_f32_e32 vcc, s2, v66
	v_mul_f32_e32 v67, 0x4b800000, v66
	v_lshl_add_u64 v[74:75], s[54:55], 1, v[74:75]
	v_cndmask_b32_e32 v66, v66, v67, vcc
	v_rsq_f32_e32 v66, v66
	v_lshl_add_u64 v[74:75], v[74:75], 0, s[14:15]
	v_lshl_add_u64 v[76:77], v[74:75], 0, v[0:1]
	s_mov_b64 s[2:3], 0x100
	v_mul_f32_e32 v67, 0x45800000, v66
	v_cndmask_b32_e32 v78, v66, v67, vcc
	v_mul_f32_e32 v66, v62, v78
	v_mul_f32_e32 v67, v63, v78
	v_cvt_pk_bf16_f32 v66, v66, v67
	v_mul_f32_e32 v67, v64, v78
	v_mul_f32_e32 v68, v65, v78
	v_cvt_pk_bf16_f32 v67, v67, v68
	v_mul_f32_e32 v68, v58, v78
	v_mul_f32_e32 v69, v59, v78
	v_cvt_pk_bf16_f32 v68, v68, v69
	v_mul_f32_e32 v69, v60, v78
	v_mul_f32_e32 v71, v61, v78
	v_cvt_pk_bf16_f32 v69, v69, v71
	global_store_dwordx4 v[76:77], v[66:69], off
	v_lshl_add_u64 v[74:75], v[74:75], 0, s[2:3]
	v_mul_f32_e32 v71, v53, v78
	v_mul_f32_e32 v66, v54, v78
	v_mul_f32_e32 v67, v55, v78
	v_cvt_pk_bf16_f32 v66, v66, v67
	v_mul_f32_e32 v67, v56, v78
	v_mul_f32_e32 v68, v57, v78
	v_cvt_pk_bf16_f32 v67, v67, v68
	v_mul_f32_e32 v68, v50, v78
	v_mul_f32_e32 v69, v51, v78
	v_cvt_pk_bf16_f32 v68, v68, v69
	v_mul_f32_e32 v69, v52, v78
	v_cvt_pk_bf16_f32 v69, v69, v71
.LBB0_1463:
	s_andn2_b64 vcc, exec, s[8:9]
	s_cbranch_vccnz .LBB0_1465
	s_mov_b32 s2, 0x800000
	s_nop 0
	s_nop 0
	v_mov_b32_e32 v66, v236
	v_fmamk_f32 v66, v66, 0x3b000000, v212
	v_cmp_gt_f32_e32 vcc, s2, v66
	v_mul_f32_e32 v67, 0x4b800000, v66
	s_movk_i32 s2, 0xc00
	v_cndmask_b32_e32 v66, v66, v67, vcc
	v_rsq_f32_e32 v66, v66
	s_nop 0
	v_mul_f32_e32 v67, 0x45800000, v66
	v_cndmask_b32_e32 v66, v66, v67, vcc
	v_mul_f32_e32 v86, 0x3dd53b94, v66
	v_lshlrev_b32_e32 v66, 5, v70
	v_ashrrev_i32_e32 v67, 31, v66
	v_lshlrev_b64 v[78:79], 2, v[66:67]
	v_lshl_add_u64 v[74:75], v[144:145], 0, v[78:79]
	v_lshl_add_u64 v[78:79], v[146:147], 0, v[78:79]
	global_load_dwordx4 v[66:69], v[74:75], off offset:16
	s_nop 0
	global_load_dwordx4 v[74:77], v[74:75], off
	s_nop 0
	global_load_dwordx4 v[82:85], v[78:79], off offset:16
	s_nop 0
	global_load_dwordx4 v[78:81], v[78:79], off
	v_pk_mul_f32 v[88:89], v[62:63], v[86:87] op_sel_hi:[1,0]
	v_pk_mul_f32 v[90:91], v[64:65], v[86:87] op_sel_hi:[1,0]
	v_pk_mul_f32 v[96:97], v[56:57], v[86:87] op_sel_hi:[1,0]
	v_pk_mul_f32 v[98:99], v[54:55], v[86:87] op_sel_hi:[1,0]
	v_pk_mul_f32 v[92:93], v[58:59], v[86:87] op_sel_hi:[1,0]
	v_pk_mul_f32 v[94:95], v[60:61], v[86:87] op_sel_hi:[1,0]
	v_pk_mul_f32 v[100:101], v[52:53], v[86:87] op_sel_hi:[1,0]
	v_pk_mul_f32 v[86:87], v[50:51], v[86:87] op_sel_hi:[1,0]
	s_waitcnt vmcnt(0)
	v_pk_mul_f32 v[108:109], v[84:85], v[100:101]
	v_pk_mul_f32 v[102:103], v[78:79], v[98:99]
	v_pk_mul_f32 v[104:105], v[80:81], v[96:97]
	v_pk_mul_f32 v[78:79], v[78:79], v[88:89]
	v_pk_mul_f32 v[80:81], v[80:81], v[90:91]
	v_pk_fma_f32 v[104:105], v[76:77], v[90:91], v[104:105] neg_lo:[0,0,1] neg_hi:[0,0,1]
	v_pk_mul_f32 v[106:107], v[82:83], v[86:87]
	v_pk_fma_f32 v[76:77], v[76:77], v[96:97], v[80:81]
	v_pk_fma_f32 v[80:81], v[74:75], v[98:99], v[78:79]
	v_pk_mul_f32 v[78:79], v[82:83], v[92:93]
	v_mov_b64_e32 v[82:83], s[44:45]
	v_mad_i64_i32 v[82:83], s[2:3], v70, s2, v[82:83]
	v_pk_fma_f32 v[102:103], v[74:75], v[88:89], v[102:103] neg_lo:[0,0,1] neg_hi:[0,0,1]
	v_pk_mul_f32 v[74:75], v[84:85], v[94:95]
	v_lshl_add_u64 v[82:83], s[0:1], 1, v[82:83]
	v_pk_fma_f32 v[108:109], v[68:69], v[94:95], v[108:109] neg_lo:[0,0,1] neg_hi:[0,0,1]
	v_pk_fma_f32 v[106:107], v[66:67], v[92:93], v[106:107] neg_lo:[0,0,1] neg_hi:[0,0,1]
	v_pk_fma_f32 v[74:75], v[68:69], v[100:101], v[74:75]
	v_pk_fma_f32 v[78:79], v[66:67], v[86:87], v[78:79]
	v_cvt_pk_bf16_f32 v66, v102, v103
	v_cvt_pk_bf16_f32 v67, v104, v105
	v_cvt_pk_bf16_f32 v68, v106, v107
	v_cvt_pk_bf16_f32 v69, v108, v109
	v_lshl_add_u64 v[84:85], v[82:83], 0, v[0:1]
	s_mov_b64 s[2:3], 0x140
	global_store_dwordx4 v[84:85], v[66:69], off offset:256
	s_nop 1
	v_cvt_pk_bf16_f32 v66, v80, v81
	v_cvt_pk_bf16_f32 v67, v76, v77
	v_cvt_pk_bf16_f32 v68, v78, v79
	v_cvt_pk_bf16_f32 v69, v74, v75
	v_lshl_add_u64 v[74:75], v[82:83], 0, s[2:3]

;     __device__ __forceinline__ float ssq8(int row, int which) const { const f32x4 a = *(const f32x4*)(ssqp + row * 16 + which * 8), b = *(const f32x4*)(ssqp + row * 16 + which * 8 + 4); return ((a[0] + a[1]) + (a[2] + a[3])) + ((b[0] + b[1]) + (b[2] + b[3])); }
;     __device__ __forceinline__ void operator()(const AccT& acc, const pg8::Unit& u, int wr, int wc, int fr, int fq) const {
;     ...
;                 if (u.pn < 4) {
;                     const float rs = rsqrtf(ssq8(row, 0) * (1.0f / 512) + EPSN) * QS_MLA;
; #pragma unroll
;                     for (int bj = 0; bj < 2; ++bj)
;                         *(u32x4*)(Qm + (size_t)row * 1536 + (2 * u.pn + bj) * 192 + wc * 32 + 8 * fq) = pack8s(acc[ai][bj][m][0], acc[ai][bj][m][1], rs);
;                 } else if (u.pn < 6) {
;                     const float rs = rsqrtf(ssq8(row, 0) * (1.0f / 512) + EPSN) * QS_MLA;
;                     const int head = 4 * (u.pn - 4) + wc;
;                     const f32x4 c0 = *(const f32x4*)(cosT + row * 32 + 8 * fq), c1 = *(const f32x4*)(cosT + row * 32 + 8 * fq + 4);
;                     const f32x4 s0 = *(const f32x4*)(sinT + row * 32 + 8 * fq), s1 = *(const f32x4*)(sinT + row * 32 + 8 * fq + 4);
;                     const f32x4 x1a = acc[ai][0][m][0] * rs, x1b = acc[ai][0][m][1] * rs, x2a = acc[ai][1][m][0] * rs, x2b = acc[ai][1][m][1] * rs;
;                     const f32x4 y1a = x1a * c0 - x2a * s0, y1b = x1b * c1 - x2b * s1, y2a = x2a * c0 + x1a * s0, y2b = x2b * c1 + x1b * s1;
;                     *(u32x4*)(Qm + (size_t)row * 1536 + head * 192 + 128 + 8 * fq) = pack8s(y1a, y1b, 1.0f);
;                     *(u32x4*)(Qm + (size_t)row * 1536 + head * 192 + 160 + 8 * fq) = pack8s(y2a, y2b, 1.0f);
;                 } else {
;                     const float rs = rsqrtf(ssq8(row, 1) * (1.0f / 512) + EPSN);
; #pragma unroll
;                     for (int bj = 0; bj < 2; ++bj)
;                         *(u32x4*)(KV + (size_t)row * 2048 + (u.pn - 6) * 256 + bj * 128 + wc * 32 + 8 * fq) = pack8s(acc[ai][bj][m][0], acc[ai][bj][m][1], rs);
.LBB0_1466:
	s_andn2_b64 vcc, exec, s[8:9]
	s_cbranch_vccnz .LBB0_1468
	s_nop 0
	s_mov_b32 s2, 0x800000
	s_ashr_i32 s57, s56, 31
	s_lshl_b32 s14, s60, 1
	s_nop 0
	s_nop 0
	v_mov_b32_e32 v66, v236
	v_fmamk_f32 v66, v66, 0x3b000000, v212
	v_cmp_gt_f32_e32 vcc, s2, v66
	v_mul_f32_e32 v67, 0x4b800000, v66
	s_movk_i32 s2, 0xc00
	v_cndmask_b32_e32 v66, v66, v67, vcc
	v_rsq_f32_e32 v66, v66
	s_nop 0
	v_mul_f32_e32 v67, 0x45800000, v66
	v_cndmask_b32_e32 v66, v66, v67, vcc
	v_mul_f32_e32 v69, 0x3dd53b94, v66
	v_mul_f32_e32 v62, v62, v69
	v_mul_f32_e32 v63, v63, v69
	v_cvt_pk_bf16_f32 v62, v62, v63
	v_mul_f32_e32 v63, v64, v69
	v_mul_f32_e32 v64, v65, v69
	v_mul_f32_e32 v58, v58, v69
	v_mul_f32_e32 v59, v59, v69
	v_cvt_pk_bf16_f32 v63, v63, v64
	v_cvt_pk_bf16_f32 v64, v58, v59
	v_mul_f32_e32 v58, v60, v69
	v_mul_f32_e32 v59, v61, v69
	v_cvt_pk_bf16_f32 v65, v58, v59
	v_mov_b64_e32 v[58:59], s[44:45]
	v_mad_i64_i32 v[58:59], s[2:3], v70, s2, v[58:59]
	v_lshl_add_u64 v[58:59], s[56:57], 1, v[58:59]
	v_lshl_add_u64 v[58:59], v[58:59], 0, s[14:15]
	s_mov_b64 s[2:3], 0x180
	v_lshl_add_u64 v[60:61], v[58:59], 0, v[0:1]
	v_mul_f32_e32 v54, v54, v69
	v_mul_f32_e32 v55, v55, v69
	v_mul_f32_e32 v50, v50, v69
	v_mul_f32_e32 v51, v51, v69
	v_lshl_add_u64 v[74:75], v[58:59], 0, s[2:3]
	global_store_dwordx4 v[60:61], v[62:65], off
	v_cvt_pk_bf16_f32 v66, v54, v55
	v_mul_f32_e32 v54, v56, v69
	v_mul_f32_e32 v55, v57, v69
	v_cvt_pk_bf16_f32 v67, v54, v55
	v_cvt_pk_bf16_f32 v68, v50, v51
	v_mul_f32_e32 v50, v52, v69
	v_mul_f32_e32 v51, v53, v69
	v_cvt_pk_bf16_f32 v69, v50, v51
.LBB0_1468:
	v_lshl_add_u64 v[50:51], v[74:75], 0, v[0:1]
	v_add_u32_e32 v54, 0x90, v152
	global_store_dwordx4 v[50:51], v[66:69], off
	v_lshlrev_b32_e32 v50, 4, v54
	v_ashrrev_i32_e32 v51, 31, v50
	v_lshl_add_u64 v[56:57], v[50:51], 2, s[4:5]
	s_and_b64 vcc, exec, s[40:41]
	s_mov_b64 s[8:9], -1
	s_cbranch_vccnz .LBB0_1474
	s_and_b64 vcc, exec, s[38:39]
	s_cbranch_vccnz .LBB0_1471
	s_mov_b32 s2, 0x800000
	v_ashrrev_i32_e32 v55, 31, v54
	s_lshl_b32 s14, s60, 1
	s_mov_b64 s[8:9], 0
	v_lshlrev_b64 v[58:59], 12, v[54:55]
	v_lshl_add_u64 v[58:59], s[46:47], 0, v[58:59]
	v_mov_b32_e32 v50, v237
	v_fmamk_f32 v50, v50, 0x3b000000, v212
	v_cmp_gt_f32_e32 vcc, s2, v50
	v_mul_f32_e32 v51, 0x4b800000, v50
	v_lshl_add_u64 v[58:59], s[54:55], 1, v[58:59]
	v_cndmask_b32_e32 v50, v50, v51, vcc
	v_rsq_f32_e32 v50, v50
	v_lshl_add_u64 v[58:59], v[58:59], 0, s[14:15]
	v_lshl_add_u64 v[60:61], v[58:59], 0, v[0:1]
	s_mov_b64 s[2:3], 0x100
	v_mul_f32_e32 v51, 0x45800000, v50
	v_cndmask_b32_e32 v62, v50, v51, vcc
	v_mul_f32_e32 v50, v46, v62
	v_mul_f32_e32 v51, v47, v62
	v_cvt_pk_bf16_f32 v50, v50, v51
	v_mul_f32_e32 v51, v48, v62
	v_mul_f32_e32 v52, v49, v62
	v_cvt_pk_bf16_f32 v51, v51, v52
	v_mul_f32_e32 v52, v42, v62
	v_mul_f32_e32 v53, v43, v62
	v_cvt_pk_bf16_f32 v52, v52, v53
	v_mul_f32_e32 v53, v44, v62
	v_mul_f32_e32 v55, v45, v62
	v_cvt_pk_bf16_f32 v53, v53, v55
	global_store_dwordx4 v[60:61], v[50:53], off
	v_lshl_add_u64 v[58:59], v[58:59], 0, s[2:3]
	v_mul_f32_e32 v55, v37, v62
	v_mul_f32_e32 v50, v38, v62
	v_mul_f32_e32 v51, v39, v62
	v_cvt_pk_bf16_f32 v50, v50, v51
	v_mul_f32_e32 v51, v40, v62
	v_mul_f32_e32 v52, v41, v62
	v_cvt_pk_bf16_f32 v51, v51, v52
	v_mul_f32_e32 v52, v34, v62
	v_mul_f32_e32 v53, v35, v62
	v_cvt_pk_bf16_f32 v52, v52, v53
	v_mul_f32_e32 v53, v36, v62
	v_cvt_pk_bf16_f32 v53, v53, v55
.LBB0_1471:
	s_andn2_b64 vcc, exec, s[8:9]
	s_cbranch_vccnz .LBB0_1473
	s_mov_b32 s2, 0x800000
	s_nop 0
	s_nop 0
	v_mov_b32_e32 v50, v237
	v_fmamk_f32 v50, v50, 0x3b000000, v212
	v_cmp_gt_f32_e32 vcc, s2, v50
	v_mul_f32_e32 v51, 0x4b800000, v50
	s_movk_i32 s2, 0xc00
	v_cndmask_b32_e32 v50, v50, v51, vcc
	v_rsq_f32_e32 v50, v50
	s_nop 0
	v_mul_f32_e32 v51, 0x45800000, v50
	v_cndmask_b32_e32 v50, v50, v51, vcc
	v_mul_f32_e32 v70, 0x3dd53b94, v50
	v_lshlrev_b32_e32 v50, 5, v54
	v_ashrrev_i32_e32 v51, 31, v50
	v_lshlrev_b64 v[62:63], 2, v[50:51]
	v_lshl_add_u64 v[58:59], v[144:145], 0, v[62:63]
	v_lshl_add_u64 v[62:63], v[146:147], 0, v[62:63]
	global_load_dwordx4 v[50:53], v[58:59], off offset:16
	s_nop 0
	global_load_dwordx4 v[58:61], v[58:59], off
	s_nop 0
	global_load_dwordx4 v[66:69], v[62:63], off offset:16
	s_nop 0
	global_load_dwordx4 v[62:65], v[62:63], off
	v_pk_mul_f32 v[72:73], v[46:47], v[70:71] op_sel_hi:[1,0]
	v_pk_mul_f32 v[74:75], v[48:49], v[70:71] op_sel_hi:[1,0]
	v_pk_mul_f32 v[80:81], v[40:41], v[70:71] op_sel_hi:[1,0]
	v_pk_mul_f32 v[82:83], v[38:39], v[70:71] op_sel_hi:[1,0]
	v_pk_mul_f32 v[76:77], v[42:43], v[70:71] op_sel_hi:[1,0]
	v_pk_mul_f32 v[78:79], v[44:45], v[70:71] op_sel_hi:[1,0]
	v_pk_mul_f32 v[84:85], v[36:37], v[70:71] op_sel_hi:[1,0]
	v_pk_mul_f32 v[70:71], v[34:35], v[70:71] op_sel_hi:[1,0]
	s_waitcnt vmcnt(0)
	v_pk_mul_f32 v[92:93], v[68:69], v[84:85]
	v_pk_mul_f32 v[86:87], v[62:63], v[82:83]
	v_pk_mul_f32 v[88:89], v[64:65], v[80:81]
	v_pk_mul_f32 v[62:63], v[62:63], v[72:73]
	v_pk_mul_f32 v[64:65], v[64:65], v[74:75]
	v_pk_fma_f32 v[88:89], v[60:61], v[74:75], v[88:89] neg_lo:[0,0,1] neg_hi:[0,0,1]
	v_pk_mul_f32 v[90:91], v[66:67], v[70:71]
	v_pk_fma_f32 v[60:61], v[60:61], v[80:81], v[64:65]
	v_pk_fma_f32 v[64:65], v[58:59], v[82:83], v[62:63]
	v_pk_mul_f32 v[62:63], v[66:67], v[76:77]
	v_mov_b64_e32 v[66:67], s[44:45]
	v_mad_i64_i32 v[66:67], s[2:3], v54, s2, v[66:67]
	v_pk_fma_f32 v[86:87], v[58:59], v[72:73], v[86:87] neg_lo:[0,0,1] neg_hi:[0,0,1]
	v_pk_mul_f32 v[58:59], v[68:69], v[78:79]
	v_lshl_add_u64 v[66:67], s[0:1], 1, v[66:67]
	v_pk_fma_f32 v[92:93], v[52:53], v[78:79], v[92:93] neg_lo:[0,0,1] neg_hi:[0,0,1]
	v_pk_fma_f32 v[90:91], v[50:51], v[76:77], v[90:91] neg_lo:[0,0,1] neg_hi:[0,0,1]
	v_pk_fma_f32 v[58:59], v[52:53], v[84:85], v[58:59]
	v_pk_fma_f32 v[62:63], v[50:51], v[70:71], v[62:63]
	v_cvt_pk_bf16_f32 v50, v86, v87
	v_cvt_pk_bf16_f32 v51, v88, v89
	v_cvt_pk_bf16_f32 v52, v90, v91
	v_cvt_pk_bf16_f32 v53, v92, v93
	v_lshl_add_u64 v[68:69], v[66:67], 0, v[0:1]
	s_mov_b64 s[2:3], 0x140
	global_store_dwordx4 v[68:69], v[50:53], off offset:256
	s_nop 1
	v_cvt_pk_bf16_f32 v50, v64, v65
	v_cvt_pk_bf16_f32 v51, v60, v61
	v_cvt_pk_bf16_f32 v52, v62, v63
	v_cvt_pk_bf16_f32 v53, v58, v59
	v_lshl_add_u64 v[58:59], v[66:67], 0, s[2:3]

;     __device__ __forceinline__ float ssq8(int row, int which) const { const f32x4 a = *(const f32x4*)(ssqp + row * 16 + which * 8), b = *(const f32x4*)(ssqp + row * 16 + which * 8 + 4); return ((a[0] + a[1]) + (a[2] + a[3])) + ((b[0] + b[1]) + (b[2] + b[3])); }
;     __device__ __forceinline__ void operator()(const AccT& acc, const pg8::Unit& u, int wr, int wc, int fr, int fq) const {
;     ...
;                 if (u.pn < 4) {
;                     const float rs = rsqrtf(ssq8(row, 0) * (1.0f / 512) + EPSN) * QS_MLA;
; #pragma unroll
;                     for (int bj = 0; bj < 2; ++bj)
;                         *(u32x4*)(Qm + (size_t)row * 1536 + (2 * u.pn + bj) * 192 + wc * 32 + 8 * fq) = pack8s(acc[ai][bj][m][0], acc[ai][bj][m][1], rs);
;                 } else if (u.pn < 6) {
;                     const float rs = rsqrtf(ssq8(row, 0) * (1.0f / 512) + EPSN) * QS_MLA;
;                     const int head = 4 * (u.pn - 4) + wc;
;                     const f32x4 c0 = *(const f32x4*)(cosT + row * 32 + 8 * fq), c1 = *(const f32x4*)(cosT + row * 32 + 8 * fq + 4);
;                     const f32x4 s0 = *(const f32x4*)(sinT + row * 32 + 8 * fq), s1 = *(const f32x4*)(sinT + row * 32 + 8 * fq + 4);
;                     const f32x4 x1a = acc[ai][0][m][0] * rs, x1b = acc[ai][0][m][1] * rs, x2a = acc[ai][1][m][0] * rs, x2b = acc[ai][1][m][1] * rs;
;                     const f32x4 y1a = x1a * c0 - x2a * s0, y1b = x1b * c1 - x2b * s1, y2a = x2a * c0 + x1a * s0, y2b = x2b * c1 + x1b * s1;
;                     *(u32x4*)(Qm + (size_t)row * 1536 + head * 192 + 128 + 8 * fq) = pack8s(y1a, y1b, 1.0f);
;                     *(u32x4*)(Qm + (size_t)row * 1536 + head * 192 + 160 + 8 * fq) = pack8s(y2a, y2b, 1.0f);
;                 } else {
;                     const float rs = rsqrtf(ssq8(row, 1) * (1.0f / 512) + EPSN);
; #pragma unroll
;                     for (int bj = 0; bj < 2; ++bj)
;                         *(u32x4*)(KV + (size_t)row * 2048 + (u.pn - 6) * 256 + bj * 128 + wc * 32 + 8 * fq) = pack8s(acc[ai][bj][m][0], acc[ai][bj][m][1], rs);
.LBB0_1474:
	s_andn2_b64 vcc, exec, s[8:9]
	s_cbranch_vccnz .LBB0_1476
	s_nop 0
	s_mov_b32 s2, 0x800000
	s_ashr_i32 s57, s56, 31
	s_lshl_b32 s14, s60, 1
	s_nop 0
	s_nop 0
	v_mov_b32_e32 v50, v237
	v_fmamk_f32 v50, v50, 0x3b000000, v212
	v_cmp_gt_f32_e32 vcc, s2, v50
	v_mul_f32_e32 v51, 0x4b800000, v50
	s_movk_i32 s2, 0xc00
	v_cndmask_b32_e32 v50, v50, v51, vcc
	v_rsq_f32_e32 v50, v50
	s_nop 0
	v_mul_f32_e32 v51, 0x45800000, v50
	v_cndmask_b32_e32 v50, v50, v51, vcc
	v_mul_f32_e32 v53, 0x3dd53b94, v50
	v_mul_f32_e32 v46, v46, v53
	v_mul_f32_e32 v47, v47, v53
	v_cvt_pk_bf16_f32 v46, v46, v47
	v_mul_f32_e32 v47, v48, v53
	v_mul_f32_e32 v48, v49, v53
	v_mul_f32_e32 v42, v42, v53
	v_mul_f32_e32 v43, v43, v53
	v_cvt_pk_bf16_f32 v47, v47, v48
	v_cvt_pk_bf16_f32 v48, v42, v43
	v_mul_f32_e32 v42, v44, v53
	v_mul_f32_e32 v43, v45, v53
	v_cvt_pk_bf16_f32 v49, v42, v43
	v_mov_b64_e32 v[42:43], s[44:45]
	v_mad_i64_i32 v[42:43], s[2:3], v54, s2, v[42:43]
	v_lshl_add_u64 v[42:43], s[56:57], 1, v[42:43]
	v_lshl_add_u64 v[42:43], v[42:43], 0, s[14:15]
	s_mov_b64 s[2:3], 0x180
	v_lshl_add_u64 v[44:45], v[42:43], 0, v[0:1]
	v_mul_f32_e32 v38, v38, v53
	v_mul_f32_e32 v39, v39, v53
	v_mul_f32_e32 v34, v34, v53
	v_mul_f32_e32 v35, v35, v53
	v_lshl_add_u64 v[58:59], v[42:43], 0, s[2:3]
	global_store_dwordx4 v[44:45], v[46:49], off
	v_cvt_pk_bf16_f32 v50, v38, v39
	v_mul_f32_e32 v38, v40, v53
	v_mul_f32_e32 v39, v41, v53
	v_cvt_pk_bf16_f32 v51, v38, v39
	v_cvt_pk_bf16_f32 v52, v34, v35
	v_mul_f32_e32 v34, v36, v53
	v_mul_f32_e32 v35, v37, v53
	v_cvt_pk_bf16_f32 v53, v34, v35
.LBB0_1476:
	v_lshl_add_u64 v[34:35], v[58:59], 0, v[0:1]
	v_add_u32_e32 v38, 0xa0, v152
	global_store_dwordx4 v[34:35], v[50:53], off
	v_lshlrev_b32_e32 v34, 4, v38
	v_ashrrev_i32_e32 v35, 31, v34
	v_lshl_add_u64 v[40:41], v[34:35], 2, s[4:5]
	s_and_b64 vcc, exec, s[40:41]
	s_mov_b64 s[8:9], -1
	s_cbranch_vccnz .LBB0_1482
	s_and_b64 vcc, exec, s[38:39]
	s_cbranch_vccnz .LBB0_1479
	s_mov_b32 s2, 0x800000
	v_ashrrev_i32_e32 v39, 31, v38
	s_lshl_b32 s14, s60, 1
	s_mov_b64 s[8:9], 0
	v_lshlrev_b64 v[42:43], 12, v[38:39]
	v_lshl_add_u64 v[42:43], s[46:47], 0, v[42:43]
	v_mov_b32_e32 v34, v238
	v_fmamk_f32 v34, v34, 0x3b000000, v212
	v_cmp_gt_f32_e32 vcc, s2, v34
	v_mul_f32_e32 v35, 0x4b800000, v34
	v_lshl_add_u64 v[42:43], s[54:55], 1, v[42:43]
	v_cndmask_b32_e32 v34, v34, v35, vcc
	v_rsq_f32_e32 v34, v34
	v_lshl_add_u64 v[42:43], v[42:43], 0, s[14:15]
	v_lshl_add_u64 v[44:45], v[42:43], 0, v[0:1]
	s_mov_b64 s[2:3], 0x100
	v_mul_f32_e32 v35, 0x45800000, v34
	v_cndmask_b32_e32 v46, v34, v35, vcc
	v_mul_f32_e32 v34, v30, v46
	v_mul_f32_e32 v35, v31, v46
	v_cvt_pk_bf16_f32 v34, v34, v35
	v_mul_f32_e32 v35, v32, v46
	v_mul_f32_e32 v36, v33, v46
	v_cvt_pk_bf16_f32 v35, v35, v36
	v_mul_f32_e32 v36, v26, v46
	v_mul_f32_e32 v37, v27, v46
	v_cvt_pk_bf16_f32 v36, v36, v37
	v_mul_f32_e32 v37, v28, v46
	v_mul_f32_e32 v39, v29, v46
	v_cvt_pk_bf16_f32 v37, v37, v39
	global_store_dwordx4 v[44:45], v[34:37], off
	v_lshl_add_u64 v[42:43], v[42:43], 0, s[2:3]
	v_mul_f32_e32 v39, v21, v46
	v_mul_f32_e32 v34, v22, v46
	v_mul_f32_e32 v35, v23, v46
	v_cvt_pk_bf16_f32 v34, v34, v35
	v_mul_f32_e32 v35, v24, v46
	v_mul_f32_e32 v36, v25, v46
	v_cvt_pk_bf16_f32 v35, v35, v36
	v_mul_f32_e32 v36, v18, v46
	v_mul_f32_e32 v37, v19, v46
	v_cvt_pk_bf16_f32 v36, v36, v37
	v_mul_f32_e32 v37, v20, v46
	v_cvt_pk_bf16_f32 v37, v37, v39
.LBB0_1479:
	s_andn2_b64 vcc, exec, s[8:9]
	s_cbranch_vccnz .LBB0_1481
	s_mov_b32 s2, 0x800000
	s_nop 0
	s_nop 0
	v_mov_b32_e32 v34, v238
	v_fmamk_f32 v34, v34, 0x3b000000, v212
	v_cmp_gt_f32_e32 vcc, s2, v34
	v_mul_f32_e32 v35, 0x4b800000, v34
	s_movk_i32 s2, 0xc00
	v_cndmask_b32_e32 v34, v34, v35, vcc
	v_rsq_f32_e32 v34, v34
	s_nop 0
	v_mul_f32_e32 v35, 0x45800000, v34
	v_cndmask_b32_e32 v34, v34, v35, vcc
	v_mul_f32_e32 v54, 0x3dd53b94, v34
	v_lshlrev_b32_e32 v34, 5, v38
	v_ashrrev_i32_e32 v35, 31, v34
	v_lshlrev_b64 v[46:47], 2, v[34:35]
	v_lshl_add_u64 v[42:43], v[144:145], 0, v[46:47]
	v_lshl_add_u64 v[46:47], v[146:147], 0, v[46:47]
	global_load_dwordx4 v[34:37], v[42:43], off offset:16
	s_nop 0
	global_load_dwordx4 v[42:45], v[42:43], off
	s_nop 0
	global_load_dwordx4 v[50:53], v[46:47], off offset:16
	s_nop 0
	global_load_dwordx4 v[46:49], v[46:47], off
	v_pk_mul_f32 v[56:57], v[30:31], v[54:55] op_sel_hi:[1,0]
	v_pk_mul_f32 v[58:59], v[32:33], v[54:55] op_sel_hi:[1,0]
	v_pk_mul_f32 v[64:65], v[24:25], v[54:55] op_sel_hi:[1,0]
	v_pk_mul_f32 v[66:67], v[22:23], v[54:55] op_sel_hi:[1,0]
	v_pk_mul_f32 v[60:61], v[26:27], v[54:55] op_sel_hi:[1,0]
	v_pk_mul_f32 v[62:63], v[28:29], v[54:55] op_sel_hi:[1,0]
	v_pk_mul_f32 v[68:69], v[20:21], v[54:55] op_sel_hi:[1,0]
	v_pk_mul_f32 v[54:55], v[18:19], v[54:55] op_sel_hi:[1,0]
	s_waitcnt vmcnt(0)
	v_pk_mul_f32 v[76:77], v[52:53], v[68:69]
	v_pk_mul_f32 v[70:71], v[46:47], v[66:67]
	v_pk_mul_f32 v[72:73], v[48:49], v[64:65]
	v_pk_mul_f32 v[46:47], v[46:47], v[56:57]
	v_pk_mul_f32 v[48:49], v[48:49], v[58:59]
	v_pk_fma_f32 v[72:73], v[44:45], v[58:59], v[72:73] neg_lo:[0,0,1] neg_hi:[0,0,1]
	v_pk_mul_f32 v[74:75], v[50:51], v[54:55]
	v_pk_fma_f32 v[44:45], v[44:45], v[64:65], v[48:49]
	v_pk_fma_f32 v[48:49], v[42:43], v[66:67], v[46:47]
	v_pk_mul_f32 v[46:47], v[50:51], v[60:61]
	v_mov_b64_e32 v[50:51], s[44:45]
	v_mad_i64_i32 v[50:51], s[2:3], v38, s2, v[50:51]
	v_pk_fma_f32 v[70:71], v[42:43], v[56:57], v[70:71] neg_lo:[0,0,1] neg_hi:[0,0,1]
	v_pk_mul_f32 v[42:43], v[52:53], v[62:63]
	v_lshl_add_u64 v[50:51], s[0:1], 1, v[50:51]
	v_pk_fma_f32 v[76:77], v[36:37], v[62:63], v[76:77] neg_lo:[0,0,1] neg_hi:[0,0,1]
	v_pk_fma_f32 v[74:75], v[34:35], v[60:61], v[74:75] neg_lo:[0,0,1] neg_hi:[0,0,1]
	v_pk_fma_f32 v[42:43], v[36:37], v[68:69], v[42:43]
	v_pk_fma_f32 v[46:47], v[34:35], v[54:55], v[46:47]
	v_cvt_pk_bf16_f32 v34, v70, v71
	v_cvt_pk_bf16_f32 v35, v72, v73
	v_cvt_pk_bf16_f32 v36, v74, v75
	v_cvt_pk_bf16_f32 v37, v76, v77
	v_lshl_add_u64 v[52:53], v[50:51], 0, v[0:1]
	s_mov_b64 s[2:3], 0x140
	global_store_dwordx4 v[52:53], v[34:37], off offset:256
	s_nop 1
	v_cvt_pk_bf16_f32 v34, v48, v49
	v_cvt_pk_bf16_f32 v35, v44, v45
	v_cvt_pk_bf16_f32 v36, v46, v47
	v_cvt_pk_bf16_f32 v37, v42, v43
	v_lshl_add_u64 v[42:43], v[50:51], 0, s[2:3]

;     __device__ __forceinline__ float ssq8(int row, int which) const { const f32x4 a = *(const f32x4*)(ssqp + row * 16 + which * 8), b = *(const f32x4*)(ssqp + row * 16 + which * 8 + 4); return ((a[0] + a[1]) + (a[2] + a[3])) + ((b[0] + b[1]) + (b[2] + b[3])); }
;     __device__ __forceinline__ void operator()(const AccT& acc, const pg8::Unit& u, int wr, int wc, int fr, int fq) const {
;     ...
;                 if (u.pn < 4) {
;                     const float rs = rsqrtf(ssq8(row, 0) * (1.0f / 512) + EPSN) * QS_MLA;
; #pragma unroll
;                     for (int bj = 0; bj < 2; ++bj)
;                         *(u32x4*)(Qm + (size_t)row * 1536 + (2 * u.pn + bj) * 192 + wc * 32 + 8 * fq) = pack8s(acc[ai][bj][m][0], acc[ai][bj][m][1], rs);
;                 } else if (u.pn < 6) {
;                     const float rs = rsqrtf(ssq8(row, 0) * (1.0f / 512) + EPSN) * QS_MLA;
;                     const int head = 4 * (u.pn - 4) + wc;
;                     const f32x4 c0 = *(const f32x4*)(cosT + row * 32 + 8 * fq), c1 = *(const f32x4*)(cosT + row * 32 + 8 * fq + 4);
;                     const f32x4 s0 = *(const f32x4*)(sinT + row * 32 + 8 * fq), s1 = *(const f32x4*)(sinT + row * 32 + 8 * fq + 4);
;                     const f32x4 x1a = acc[ai][0][m][0] * rs, x1b = acc[ai][0][m][1] * rs, x2a = acc[ai][1][m][0] * rs, x2b = acc[ai][1][m][1] * rs;
;                     const f32x4 y1a = x1a * c0 - x2a * s0, y1b = x1b * c1 - x2b * s1, y2a = x2a * c0 + x1a * s0, y2b = x2b * c1 + x1b * s1;
;                     *(u32x4*)(Qm + (size_t)row * 1536 + head * 192 + 128 + 8 * fq) = pack8s(y1a, y1b, 1.0f);
;                     *(u32x4*)(Qm + (size_t)row * 1536 + head * 192 + 160 + 8 * fq) = pack8s(y2a, y2b, 1.0f);
;                 } else {
;                     const float rs = rsqrtf(ssq8(row, 1) * (1.0f / 512) + EPSN);
; #pragma unroll
;                     for (int bj = 0; bj < 2; ++bj)
;                         *(u32x4*)(KV + (size_t)row * 2048 + (u.pn - 6) * 256 + bj * 128 + wc * 32 + 8 * fq) = pack8s(acc[ai][bj][m][0], acc[ai][bj][m][1], rs);
.LBB0_1482:
	s_andn2_b64 vcc, exec, s[8:9]
	s_cbranch_vccnz .LBB0_1484
	s_nop 0
	s_mov_b32 s2, 0x800000
	s_ashr_i32 s57, s56, 31
	s_lshl_b32 s14, s60, 1
	s_nop 0
	s_nop 0
	v_mov_b32_e32 v34, v238
	v_fmamk_f32 v34, v34, 0x3b000000, v212
	v_cmp_gt_f32_e32 vcc, s2, v34
	v_mul_f32_e32 v35, 0x4b800000, v34
	s_movk_i32 s2, 0xc00
	v_cndmask_b32_e32 v34, v34, v35, vcc
	v_rsq_f32_e32 v34, v34
	s_nop 0
	v_mul_f32_e32 v35, 0x45800000, v34
	v_cndmask_b32_e32 v34, v34, v35, vcc
	v_mul_f32_e32 v37, 0x3dd53b94, v34
	v_mul_f32_e32 v30, v30, v37
	v_mul_f32_e32 v31, v31, v37
	v_cvt_pk_bf16_f32 v30, v30, v31
	v_mul_f32_e32 v31, v32, v37
	v_mul_f32_e32 v32, v33, v37
	v_mul_f32_e32 v26, v26, v37
	v_mul_f32_e32 v27, v27, v37
	v_cvt_pk_bf16_f32 v31, v31, v32
	v_cvt_pk_bf16_f32 v32, v26, v27
	v_mul_f32_e32 v26, v28, v37
	v_mul_f32_e32 v27, v29, v37
	v_cvt_pk_bf16_f32 v33, v26, v27
	v_mov_b64_e32 v[26:27], s[44:45]
	v_mad_i64_i32 v[26:27], s[2:3], v38, s2, v[26:27]
	v_lshl_add_u64 v[26:27], s[56:57], 1, v[26:27]
	v_lshl_add_u64 v[26:27], v[26:27], 0, s[14:15]
	s_mov_b64 s[2:3], 0x180
	v_lshl_add_u64 v[28:29], v[26:27], 0, v[0:1]
	v_mul_f32_e32 v22, v22, v37
	v_mul_f32_e32 v23, v23, v37
	v_mul_f32_e32 v18, v18, v37
	v_mul_f32_e32 v19, v19, v37
	v_lshl_add_u64 v[42:43], v[26:27], 0, s[2:3]
	global_store_dwordx4 v[28:29], v[30:33], off
	v_cvt_pk_bf16_f32 v34, v22, v23
	v_mul_f32_e32 v22, v24, v37
	v_mul_f32_e32 v23, v25, v37
	v_cvt_pk_bf16_f32 v35, v22, v23
	v_cvt_pk_bf16_f32 v36, v18, v19
	v_mul_f32_e32 v18, v20, v37
	v_mul_f32_e32 v19, v21, v37
	v_cvt_pk_bf16_f32 v37, v18, v19
.LBB0_1484:
	v_lshl_add_u64 v[18:19], v[42:43], 0, v[0:1]
	v_add_u32_e32 v22, 0xb0, v152
	global_store_dwordx4 v[18:19], v[34:37], off
	v_lshlrev_b32_e32 v18, 4, v22
	v_ashrrev_i32_e32 v19, 31, v18
	v_lshl_add_u64 v[24:25], v[18:19], 2, s[4:5]
	s_and_b64 vcc, exec, s[40:41]
	s_mov_b64 s[8:9], -1
	s_cbranch_vccnz .LBB0_1490
	s_and_b64 vcc, exec, s[38:39]
	s_cbranch_vccnz .LBB0_1487
	s_mov_b32 s2, 0x800000
	v_ashrrev_i32_e32 v23, 31, v22
	v_lshlrev_b64 v[30:31], 12, v[22:23]
	v_lshl_add_u64 v[30:31], s[46:47], 0, v[30:31]
	s_lshl_b32 s14, s60, 1
	v_lshl_add_u64 v[30:31], s[54:55], 1, v[30:31]
	s_mov_b64 s[8:9], 0
	s_nop 0
	s_nop 0
	v_mov_b32_e32 v18, v239
	v_fmamk_f32 v18, v18, 0x3b000000, v212
	v_mul_f32_e32 v19, 0x4b800000, v18
	v_cmp_gt_f32_e32 vcc, s2, v18
	s_mov_b64 s[2:3], 0x100
	s_nop 0
	v_cndmask_b32_e32 v18, v18, v19, vcc
	v_rsq_f32_e32 v20, v18
	v_lshl_add_u64 v[18:19], v[30:31], 0, s[14:15]
	v_lshl_add_u64 v[28:29], v[18:19], 0, v[0:1]
	v_lshl_add_u64 v[26:27], v[18:19], 0, s[2:3]
	v_mul_f32_e32 v18, 0x45800000, v20
	v_cndmask_b32_e32 v18, v20, v18, vcc
	v_mul_f32_e32 v19, v14, v18
	v_mul_f32_e32 v20, v15, v18
	v_mul_f32_e32 v21, v16, v18
	v_mul_f32_e32 v23, v17, v18
	v_mul_f32_e32 v30, v10, v18
	v_mul_f32_e32 v31, v11, v18
	v_mul_f32_e32 v32, v12, v18
	v_mul_f32_e32 v33, v13, v18
	v_mul_f32_e32 v34, v6, v18
	v_mul_f32_e32 v35, v7, v18
	v_mul_f32_e32 v36, v8, v18
	v_mul_f32_e32 v37, v9, v18
	v_mul_f32_e32 v38, v2, v18
	v_mul_f32_e32 v39, v3, v18
	v_mul_f32_e32 v40, v4, v18
	v_mul_f32_e32 v41, v5, v18
	v_cvt_pk_bf16_f32 v18, v19, v20
	v_cvt_pk_bf16_f32 v19, v21, v23
	v_cvt_pk_bf16_f32 v20, v30, v31
	v_cvt_pk_bf16_f32 v21, v32, v33
	global_store_dwordx4 v[28:29], v[18:21], off
	s_nop 1
	v_cvt_pk_bf16_f32 v18, v34, v35
	v_cvt_pk_bf16_f32 v19, v36, v37
	v_cvt_pk_bf16_f32 v20, v38, v39
	v_cvt_pk_bf16_f32 v21, v40, v41
.LBB0_1487:
	s_andn2_b64 vcc, exec, s[8:9]
	s_cbranch_vccnz .LBB0_1489
	s_mov_b32 s2, 0x800000
	s_nop 0
	s_nop 0
	v_mov_b32_e32 v18, v239
	v_fmamk_f32 v18, v18, 0x3b000000, v212
	v_cmp_gt_f32_e32 vcc, s2, v18
	v_mul_f32_e32 v19, 0x4b800000, v18
	s_movk_i32 s2, 0xc00
	v_cndmask_b32_e32 v18, v18, v19, vcc
	v_rsq_f32_e32 v18, v18
	s_nop 0
	v_mul_f32_e32 v19, 0x45800000, v18
	v_cndmask_b32_e32 v18, v18, v19, vcc
	v_mul_f32_e32 v38, 0x3dd53b94, v18
	v_lshlrev_b32_e32 v18, 5, v22
	v_ashrrev_i32_e32 v19, 31, v18
	v_lshlrev_b64 v[30:31], 2, v[18:19]
	v_lshl_add_u64 v[26:27], v[144:145], 0, v[30:31]
	v_lshl_add_u64 v[30:31], v[146:147], 0, v[30:31]
	global_load_dwordx4 v[18:21], v[26:27], off offset:16
	s_nop 0
	global_load_dwordx4 v[26:29], v[26:27], off
	s_nop 0
	global_load_dwordx4 v[34:37], v[30:31], off offset:16
	s_nop 0
	global_load_dwordx4 v[30:33], v[30:31], off
	v_pk_mul_f32 v[40:41], v[14:15], v[38:39] op_sel_hi:[1,0]
	v_pk_mul_f32 v[42:43], v[16:17], v[38:39] op_sel_hi:[1,0]
	v_pk_mul_f32 v[48:49], v[8:9], v[38:39] op_sel_hi:[1,0]
	v_pk_mul_f32 v[50:51], v[6:7], v[38:39] op_sel_hi:[1,0]
	v_pk_mul_f32 v[44:45], v[10:11], v[38:39] op_sel_hi:[1,0]
	v_pk_mul_f32 v[46:47], v[12:13], v[38:39] op_sel_hi:[1,0]
	v_pk_mul_f32 v[52:53], v[4:5], v[38:39] op_sel_hi:[1,0]
	v_pk_mul_f32 v[38:39], v[2:3], v[38:39] op_sel_hi:[1,0]
	s_waitcnt vmcnt(0)
	v_pk_mul_f32 v[60:61], v[36:37], v[52:53]
	v_pk_mul_f32 v[54:55], v[30:31], v[50:51]
	v_pk_mul_f32 v[56:57], v[32:33], v[48:49]
	v_pk_mul_f32 v[30:31], v[30:31], v[40:41]
	v_pk_mul_f32 v[32:33], v[32:33], v[42:43]
	v_pk_fma_f32 v[56:57], v[28:29], v[42:43], v[56:57] neg_lo:[0,0,1] neg_hi:[0,0,1]
	v_pk_mul_f32 v[58:59], v[34:35], v[38:39]
	v_pk_fma_f32 v[28:29], v[28:29], v[48:49], v[32:33]
	v_pk_fma_f32 v[32:33], v[26:27], v[50:51], v[30:31]
	v_pk_mul_f32 v[30:31], v[34:35], v[44:45]
	v_mov_b64_e32 v[34:35], s[44:45]
	v_mad_i64_i32 v[34:35], s[2:3], v22, s2, v[34:35]
	v_pk_fma_f32 v[54:55], v[26:27], v[40:41], v[54:55] neg_lo:[0,0,1] neg_hi:[0,0,1]
	v_pk_mul_f32 v[26:27], v[36:37], v[46:47]
	v_lshl_add_u64 v[34:35], s[0:1], 1, v[34:35]
	v_pk_fma_f32 v[60:61], v[20:21], v[46:47], v[60:61] neg_lo:[0,0,1] neg_hi:[0,0,1]
	v_pk_fma_f32 v[58:59], v[18:19], v[44:45], v[58:59] neg_lo:[0,0,1] neg_hi:[0,0,1]
	v_pk_fma_f32 v[26:27], v[20:21], v[52:53], v[26:27]
	v_pk_fma_f32 v[30:31], v[18:19], v[38:39], v[30:31]
	v_cvt_pk_bf16_f32 v18, v54, v55
	v_cvt_pk_bf16_f32 v19, v56, v57
	v_cvt_pk_bf16_f32 v20, v58, v59
	v_cvt_pk_bf16_f32 v21, v60, v61
	v_lshl_add_u64 v[36:37], v[34:35], 0, v[0:1]
	s_mov_b64 s[0:1], 0x140
	global_store_dwordx4 v[36:37], v[18:21], off offset:256
	s_nop 1
	v_cvt_pk_bf16_f32 v18, v32, v33
	v_cvt_pk_bf16_f32 v19, v28, v29
	v_cvt_pk_bf16_f32 v20, v30, v31
	v_cvt_pk_bf16_f32 v21, v26, v27
	v_lshl_add_u64 v[26:27], v[34:35], 0, s[0:1]

;     __device__ __forceinline__ float ssq8(int row, int which) const { const f32x4 a = *(const f32x4*)(ssqp + row * 16 + which * 8), b = *(const f32x4*)(ssqp + row * 16 + which * 8 + 4); return ((a[0] + a[1]) + (a[2] + a[3])) + ((b[0] + b[1]) + (b[2] + b[3])); }
;     __device__ __forceinline__ void operator()(const AccT& acc, const pg8::Unit& u, int wr, int wc, int fr, int fq) const {
;         const int row0 = u.pm * 256 + wr * 64 + fr;
; #pragma unroll
;         for (int ai = 0; ai < 2; ++ai)
; #pragma unroll
;             for (int m = 0; m < 4; ++m) {
;                 const int row = row0 + ai * 128 + m * 16;
;                 if (u.pn < 4) {
;                     const float rs = rsqrtf(ssq8(row, 0) * (1.0f / 512) + EPSN) * QS_MLA;
; #pragma unroll
;                     for (int bj = 0; bj < 2; ++bj)
;                         *(u32x4*)(Qm + (size_t)row * 1536 + (2 * u.pn + bj) * 192 + wc * 32 + 8 * fq) = pack8s(acc[ai][bj][m][0], acc[ai][bj][m][1], rs);
;                 } else if (u.pn < 6) {
;                     const float rs = rsqrtf(ssq8(row, 0) * (1.0f / 512) + EPSN) * QS_MLA;
;                     const int head = 4 * (u.pn - 4) + wc;
;                     const f32x4 c0 = *(const f32x4*)(cosT + row * 32 + 8 * fq), c1 = *(const f32x4*)(cosT + row * 32 + 8 * fq + 4);
;                     const f32x4 s0 = *(const f32x4*)(sinT + row * 32 + 8 * fq), s1 = *(const f32x4*)(sinT + row * 32 + 8 * fq + 4);
;                     const f32x4 x1a = acc[ai][0][m][0] * rs, x1b = acc[ai][0][m][1] * rs, x2a = acc[ai][1][m][0] * rs, x2b = acc[ai][1][m][1] * rs;
;                     const f32x4 y1a = x1a * c0 - x2a * s0, y1b = x1b * c1 - x2b * s1, y2a = x2a * c0 + x1a * s0, y2b = x2b * c1 + x1b * s1;
;                     *(u32x4*)(Qm + (size_t)row * 1536 + head * 192 + 128 + 8 * fq) = pack8s(y1a, y1b, 1.0f);
;                     *(u32x4*)(Qm + (size_t)row * 1536 + head * 192 + 160 + 8 * fq) = pack8s(y2a, y2b, 1.0f);
;                 } else {
;                     const float rs = rsqrtf(ssq8(row, 1) * (1.0f / 512) + EPSN);
; #pragma unroll
;                     for (int bj = 0; bj < 2; ++bj)
;                         *(u32x4*)(KV + (size_t)row * 2048 + (u.pn - 6) * 256 + bj * 128 + wc * 32 + 8 * fq) = pack8s(acc[ai][bj][m][0], acc[ai][bj][m][1], rs);
;                 }
;             }
;     }
.LBB0_1490:
	s_andn2_b64 vcc, exec, s[8:9]
	s_cbranch_vccnz .LBB0_1417
	s_nop 0
	s_mov_b32 s0, 0x800000
	s_ashr_i32 s57, s56, 31
	s_lshl_b32 s14, s60, 1
	s_nop 0
	s_nop 0
	v_mov_b32_e32 v18, v239
	v_fmamk_f32 v18, v18, 0x3b000000, v212
	v_cmp_gt_f32_e32 vcc, s0, v18
	v_mul_f32_e32 v19, 0x4b800000, v18
	s_movk_i32 s0, 0xc00
	v_cndmask_b32_e32 v18, v18, v19, vcc
	v_rsq_f32_e32 v18, v18
	s_nop 0
	v_mul_f32_e32 v19, 0x45800000, v18
	v_cndmask_b32_e32 v18, v18, v19, vcc
	v_mul_f32_e32 v21, 0x3dd53b94, v18
	v_mul_f32_e32 v14, v14, v21
	v_mul_f32_e32 v15, v15, v21
	v_cvt_pk_bf16_f32 v14, v14, v15
	v_mul_f32_e32 v15, v16, v21
	v_mul_f32_e32 v16, v17, v21
	v_mul_f32_e32 v10, v10, v21
	v_mul_f32_e32 v11, v11, v21
	v_cvt_pk_bf16_f32 v15, v15, v16
	v_cvt_pk_bf16_f32 v16, v10, v11
	v_mul_f32_e32 v10, v12, v21
	v_mul_f32_e32 v11, v13, v21
	v_cvt_pk_bf16_f32 v17, v10, v11
	v_mov_b64_e32 v[10:11], s[44:45]
	v_mad_i64_i32 v[10:11], s[0:1], v22, s0, v[10:11]
	v_lshl_add_u64 v[10:11], s[56:57], 1, v[10:11]
	v_lshl_add_u64 v[10:11], v[10:11], 0, s[14:15]
	s_mov_b64 s[0:1], 0x180
	v_lshl_add_u64 v[12:13], v[10:11], 0, v[0:1]
	v_mul_f32_e32 v6, v6, v21
	v_mul_f32_e32 v7, v7, v21
	v_mul_f32_e32 v2, v2, v21
	v_mul_f32_e32 v3, v3, v21
	v_lshl_add_u64 v[26:27], v[10:11], 0, s[0:1]
	global_store_dwordx4 v[12:13], v[14:17], off
	v_cvt_pk_bf16_f32 v18, v6, v7
	v_mul_f32_e32 v6, v8, v21
	v_mul_f32_e32 v7, v9, v21
	v_cvt_pk_bf16_f32 v19, v6, v7
	v_cvt_pk_bf16_f32 v20, v2, v3
	v_mul_f32_e32 v2, v4, v21
	v_mul_f32_e32 v3, v5, v21
	v_cvt_pk_bf16_f32 v21, v2, v3
	s_branch .LBB0_1417
